# v21 plus rmsnorm gain vectors hoisted out of the row loop (three bf16 norm phases) and mix-out sample-row split-K loads requested per pass
# speedup vs baseline: 1.0019x; 1.0019x over previous
; __device__ __forceinline__ int fresh_tid() { int t = threadIdx.x; asm volatile("" : "+v"(t)); return t; }
; __device__ __forceinline__ int fresh_bid() { int t = blockIdx.x; asm volatile("" : "+s"(t)); return t; }
; __device__ __forceinline__ void norm_rows(const XSrc src, const float* gain, bf16_t* dbf, float* df32) {
;     const int lane = fresh_tid() & 63, gw = fresh_bid() * 8 + (fresh_tid() >> 6), nw = gridDim.x * 8;
;     for (int row = gw; row < MROWS; row += 2 * nw) {
;         const int row2 = row + nw < MROWS ? row + nw : row;
;         const float* xp = src.row(row); const float* xq = src.row(row2);
;         f32x4 v[8], u[8]; float ss = 0.f, st = 0.f;
; #pragma unroll
;         for (int i = 0; i < 8; ++i) { v[i] = *(const f32x4*)(xp + i * 256 + lane * 4); u[i] = *(const f32x4*)(xq + i * 256 + lane * 4); }
.LBB0_140:
	s_or_b64 exec, exec, s[14:15]
	v_mov_b32_e32 v1, v176
	s_mov_b32 s4, s94
	v_mov_b32_e32 v2, v176
	s_movk_i32 s14, 0x2080
	v_ashrrev_i32_e32 v2, 6, v2
	v_lshl_add_u32 v84, s4, 3, v2
	v_cmp_gt_i32_e32 vcc, s14, v84
	v_mbcnt_lo_u32_b32 v94, -1, 0
	s_and_saveexec_b64 s[8:9], vcc
	s_cbranch_execz .LBB0_159
	s_load_dwordx4 s[4:7], s[12:13], 0x0
	s_load_dwordx2 s[10:11], s[12:13], 0x30
	v_lshlrev_b32_e32 v1, 2, v1
	v_and_b32_e32 v2, 0xfc, v1
	v_mov_b32_e32 v71, 0
	v_mbcnt_hi_u32_b32 v3, -1, v94
	v_lshlrev_b32_e32 v70, 2, v2
	v_and_b32_e32 v1, 64, v3
	s_waitcnt lgkmcnt(0)
	v_lshl_add_u64 v[72:73], s[10:11], 0, v[70:71]
	v_lshlrev_b32_e32 v70, 1, v2
	v_add_u32_e32 v6, 64, v1
	v_lshl_add_u64 v[4:5], v[60:61], 0, v[70:71]
	s_mov_b64 s[10:11], 0x12200000
	v_xor_b32_e32 v1, 32, v3
	v_lshl_add_u64 v[74:75], v[4:5], 0, s[10:11]
	v_cmp_lt_i32_e32 vcc, v1, v6
	v_xor_b32_e32 v4, 16, v3
	s_mov_b64 s[10:11], 0x1000
	v_cndmask_b32_e32 v1, v3, v1, vcc
	v_cmp_lt_i32_e32 vcc, v4, v6
	v_lshl_add_u64 v[76:77], v[72:73], 0, s[10:11]
	s_mov_b64 s[10:11], 0x1400
	v_cndmask_b32_e32 v4, v3, v4, vcc
	v_lshlrev_b32_e32 v95, 2, v4
	v_xor_b32_e32 v4, 8, v3
	v_cmp_lt_i32_e32 vcc, v4, v6
	v_lshl_add_u64 v[78:79], v[72:73], 0, s[10:11]
	s_mov_b64 s[10:11], 0x1800
	v_cndmask_b32_e32 v4, v3, v4, vcc
	v_lshlrev_b32_e32 v96, 2, v4
	v_xor_b32_e32 v4, 4, v3
	v_cmp_lt_i32_e32 vcc, v4, v6
	v_lshl_add_u64 v[80:81], v[72:73], 0, s[10:11]
	s_mov_b64 s[10:11], 0x1c00
	v_cndmask_b32_e32 v4, v3, v4, vcc
	v_lshlrev_b32_e32 v97, 2, v4
	v_xor_b32_e32 v4, 2, v3
	v_cmp_lt_i32_e32 vcc, v4, v6
	s_lshl_b32 s3, s3, 3
	v_lshlrev_b32_e32 v1, 2, v1
	v_cndmask_b32_e32 v4, v3, v4, vcc
	v_lshlrev_b32_e32 v98, 2, v4
	v_xor_b32_e32 v4, 1, v3
	v_cmp_lt_i32_e32 vcc, v4, v6
	v_lshl_add_u64 v[82:83], v[72:73], 0, s[10:11]
	s_mov_b64 s[10:11], 0
	v_cndmask_b32_e32 v3, v3, v4, vcc
	v_lshlrev_b32_e32 v99, 2, v3
	s_movk_i32 s12, 0x2000
	v_mov_b32_e32 v100, s7
	v_mov_b32_e32 v101, s5
	v_mov_b32_e32 v102, s6
	v_mov_b32_e32 v103, s4
	v_lshlrev_b32_e32 v70, 2, v2
	s_movk_i32 s13, 0x1000
	v_mov_b32_e32 v104, 0x358637bd
	s_mov_b32 s15, 0xf800000
	v_mov_b32_e32 v105, 0x260
	s_movk_i32 s16, 0x207f
	global_load_dwordx4 v[196:199], v[72:73], off
	global_load_dwordx4 v[200:203], v[72:73], off offset:1024
	global_load_dwordx4 v[204:207], v[72:73], off offset:2048
	global_load_dwordx4 v[208:211], v[72:73], off offset:3072
	global_load_dwordx4 v[212:215], v[76:77], off
	global_load_dwordx4 v[216:219], v[78:79], off
	global_load_dwordx4 v[220:223], v[80:81], off
	global_load_dwordx4 v[224:227], v[82:83], off
	s_branch .LBB0_143

; __device__ __forceinline__ void norm_rows(const XSrc src, const float* gain, bf16_t* dbf, float* df32) {
;     ...
;     for (int row = gw; row < MROWS; row += 2 * nw) {
;         const int row2 = row + nw < MROWS ? row + nw : row;
;         const float* xp = src.row(row); const float* xq = src.row(row2);
;         f32x4 v[8], u[8]; float ss = 0.f, st = 0.f;
; #pragma unroll
;         for (int i = 0; i < 8; ++i) { v[i] = *(const f32x4*)(xp + i * 256 + lane * 4); u[i] = *(const f32x4*)(xq + i * 256 + lane * 4); }
; #pragma unroll
;         for (int i = 0; i < 8; ++i) { ss += v[i][0] * v[i][0] + v[i][1] * v[i][1] + v[i][2] * v[i][2] + v[i][3] * v[i][3]; st += u[i][0] * u[i][0] + u[i][1] * u[i][1] + u[i][2] * u[i][2] + u[i][3] * u[i][3]; }
; #pragma unroll
;         for (int o = 32; o > 0; o >>= 1) { ss += __shfl_xor(ss, o); st += __shfl_xor(st, o); }
;         const float rs = 1.0f / sqrtf(ss * (1.0f / DM) + 1e-6f), rt = 1.0f / sqrtf(st * (1.0f / DM) + 1e-6f);
.LBB0_143:
	v_add_u32_e32 v2, 0xffffe000, v84
	v_ashrrev_i32_e32 v85, 31, v84
	v_cmp_gt_i32_e32 vcc, s12, v84
	v_add_u32_e32 v106, s3, v84
	s_nop 0
	v_cndmask_b32_e32 v3, 0, v85, vcc
	v_cndmask_b32_e32 v2, v2, v84, vcc
	v_cndmask_b32_e32 v5, v100, v101, vcc
	v_cndmask_b32_e32 v4, v102, v103, vcc
	v_lshlrev_b64 v[2:3], 13, v[2:3]
	v_lshl_add_u64 v[2:3], v[4:5], 0, v[2:3]
	v_lshl_add_u64 v[6:7], v[2:3], 0, v[70:71]
	v_add_co_u32_e32 v66, vcc, s13, v6
	s_nop 1
	v_addc_co_u32_e32 v67, vcc, 0, v7, vcc
	global_load_dwordx4 v[22:25], v[6:7], off
	global_load_dwordx4 v[50:53], v[6:7], off offset:1024
	global_load_dwordx4 v[46:49], v[6:7], off offset:2048
	global_load_dwordx4 v[34:37], v[6:7], off offset:3072
	global_load_dwordx4 v[10:13], v[66:67], off offset:2048
	global_load_dwordx4 v[2:5], v[66:67], off offset:3072
	v_cmp_gt_i32_e32 vcc, s14, v106
	global_load_dwordx4 v[30:33], v[66:67], off
	s_waitcnt vmcnt(6)
	v_mul_f32_e32 v107, v23, v23
	v_cndmask_b32_e32 v86, v84, v106, vcc
	v_add_u32_e32 v6, 0xffffe000, v86
	v_ashrrev_i32_e32 v87, 31, v86
	v_cmp_gt_i32_e32 vcc, s12, v86
	s_waitcnt vmcnt(5)
	v_mul_f32_e32 v112, v51, v51
	s_waitcnt vmcnt(4)
	v_mul_f32_e32 v113, v47, v47
	v_cndmask_b32_e32 v7, 0, v87, vcc
	v_cndmask_b32_e32 v6, v6, v86, vcc
	v_cndmask_b32_e32 v9, v100, v101, vcc
	v_cndmask_b32_e32 v8, v102, v103, vcc
	v_lshlrev_b64 v[6:7], 13, v[6:7]
	v_lshl_add_u64 v[6:7], v[8:9], 0, v[6:7]
	v_lshl_add_u64 v[68:69], v[6:7], 0, v[70:71]
	v_add_co_u32_e32 v88, vcc, s13, v68
	v_fmac_f32_e32 v107, v22, v22
	s_nop 0
	v_addc_co_u32_e32 v89, vcc, 0, v69, vcc
	global_load_dwordx4 v[14:17], v[88:89], off offset:2048
	global_load_dwordx4 v[6:9], v[88:89], off offset:3072
	global_load_dwordx4 v[18:21], v[66:67], off offset:1024
	global_load_dwordx4 v[62:65], v[68:69], off
	global_load_dwordx4 v[58:61], v[68:69], off offset:1024
	global_load_dwordx4 v[54:57], v[68:69], off offset:2048
	global_load_dwordx4 v[42:45], v[68:69], off offset:3072
	global_load_dwordx4 v[38:41], v[88:89], off
	global_load_dwordx4 v[26:29], v[88:89], off offset:1024
	s_waitcnt vmcnt(11)
	v_mov_b32_e32 v68, v11
	s_waitcnt vmcnt(10)
	v_mov_b32_e32 v69, v3
	v_mov_b32_e32 v66, v10
	v_mov_b32_e32 v67, v2
	v_fmac_f32_e32 v112, v50, v50
	v_pk_mul_f32 v[68:69], v[68:69], v[68:69]
	v_mul_f32_e32 v114, v35, v35
	v_mov_b32_e32 v88, v12
	v_mov_b32_e32 v89, v4
	v_fmac_f32_e32 v113, v46, v46
	v_fmac_f32_e32 v107, v24, v24
	v_fmac_f32_e32 v112, v52, v52
	v_pk_fma_f32 v[66:67], v[66:67], v[66:67], v[68:69]
	v_fmac_f32_e32 v114, v34, v34
	v_fmac_f32_e32 v113, v48, v48
	v_fmac_f32_e32 v107, v25, v25
	v_fmac_f32_e32 v112, v53, v53
	v_pk_fma_f32 v[66:67], v[88:89], v[88:89], v[66:67]
	v_fmac_f32_e32 v114, v36, v36
	v_fmac_f32_e32 v113, v49, v49
	v_mov_b32_e32 v90, v13
	v_mov_b32_e32 v91, v5
	s_waitcnt vmcnt(9)
	v_mul_f32_e32 v115, v31, v31
	v_fmac_f32_e32 v114, v37, v37
	v_fmac_f32_e32 v115, v30, v30
	v_pk_fma_f32 v[66:67], v[90:91], v[90:91], v[66:67]
	v_fmac_f32_e32 v115, v32, v32
	v_fmac_f32_e32 v115, v33, v33
	s_waitcnt vmcnt(8)
	v_mov_b32_e32 v92, v15
	s_waitcnt vmcnt(7)
	v_mov_b32_e32 v93, v7
	v_mov_b32_e32 v68, v14
	v_mov_b32_e32 v69, v6
	v_pk_mul_f32 v[88:89], v[92:93], v[92:93]
	v_mov_b32_e32 v108, v16
	v_mov_b32_e32 v109, v8
	v_add_f32_e32 v92, v107, v112
	v_pk_fma_f32 v[68:69], v[68:69], v[68:69], v[88:89]
	v_mov_b32_e32 v110, v17
	v_mov_b32_e32 v111, v9
	v_add_f32_e32 v88, v92, v113
	v_pk_fma_f32 v[68:69], v[108:109], v[108:109], v[68:69]
	v_add_f32_e32 v90, v88, v114
	v_pk_fma_f32 v[88:89], v[110:111], v[110:111], v[68:69]
	s_waitcnt vmcnt(6)
	v_mul_f32_e32 v69, v19, v19
	v_fmac_f32_e32 v69, v18, v18
	v_fmac_f32_e32 v69, v20, v20
	v_add_f32_e32 v68, v90, v115
	v_fmac_f32_e32 v69, v21, v21
	v_add_f32_e32 v68, v68, v69
	v_add_f32_e32 v66, v68, v66
	v_add_f32_e32 v66, v66, v67
	ds_bpermute_b32 v69, v1, v66
	s_waitcnt vmcnt(5)
	v_mul_f32_e32 v67, v63, v63
	s_waitcnt vmcnt(4)
	v_mul_f32_e32 v68, v59, v59
	v_fmac_f32_e32 v67, v62, v62
	v_fmac_f32_e32 v68, v58, v58
	s_waitcnt lgkmcnt(0)
	v_add_f32_e32 v66, v66, v69
	ds_bpermute_b32 v69, v95, v66
	v_fmac_f32_e32 v67, v64, v64
	v_fmac_f32_e32 v68, v60, v60
	v_fmac_f32_e32 v67, v65, v65
	v_fmac_f32_e32 v68, v61, v61
	s_waitcnt lgkmcnt(0)
	v_add_f32_e32 v66, v66, v69
	v_add_f32_e32 v67, v67, v68
	s_waitcnt vmcnt(3)
	v_mul_f32_e32 v68, v55, v55
	ds_bpermute_b32 v69, v96, v66
	v_fmac_f32_e32 v68, v54, v54
	v_fmac_f32_e32 v68, v56, v56
	v_fmac_f32_e32 v68, v57, v57
	v_add_f32_e32 v67, v67, v68
	s_waitcnt vmcnt(2)
	v_mul_f32_e32 v68, v43, v43
	v_fmac_f32_e32 v68, v42, v42
	s_waitcnt lgkmcnt(0)
	v_add_f32_e32 v66, v66, v69
	v_fmac_f32_e32 v68, v44, v44
	ds_bpermute_b32 v69, v97, v66
	v_fmac_f32_e32 v68, v45, v45
	v_add_f32_e32 v67, v67, v68
	s_waitcnt vmcnt(1)
	v_mul_f32_e32 v68, v39, v39
	v_fmac_f32_e32 v68, v38, v38
	v_fmac_f32_e32 v68, v40, v40
	v_fmac_f32_e32 v68, v41, v41
	s_waitcnt lgkmcnt(0)
	v_add_f32_e32 v66, v66, v69
	v_add_f32_e32 v67, v67, v68
	ds_bpermute_b32 v68, v98, v66
	s_waitcnt vmcnt(0)
	v_mul_f32_e32 v69, v27, v27
	v_fmac_f32_e32 v69, v26, v26
	v_fmac_f32_e32 v69, v28, v28
	v_fmac_f32_e32 v69, v29, v29
	s_waitcnt lgkmcnt(0)
	v_add_f32_e32 v90, v66, v68
	v_add_f32_e32 v66, v67, v69
	v_add_f32_e32 v88, v66, v88
	ds_bpermute_b32 v91, v99, v90
	v_add_f32_e32 v88, v88, v89
	s_waitcnt lgkmcnt(0)
	v_add_f32_e32 v89, v90, v91
	ds_bpermute_b32 v91, v1, v88
	v_fmamk_f32 v89, v89, 0x3a000000, v104
	v_mul_f32_e32 v90, 0x4f800000, v89
	v_cmp_gt_f32_e32 vcc, s15, v89
	s_waitcnt lgkmcnt(0)
	v_add_f32_e32 v88, v88, v91
	ds_bpermute_b32 v91, v95, v88
	v_cndmask_b32_e32 v89, v89, v90, vcc
	v_sqrt_f32_e32 v90, v89
	s_waitcnt lgkmcnt(0)
; __device__ __forceinline__ unsigned cvt_pk_bf16(float lo, float hi) { const f32x2 v = {lo, hi}; const bf16x2_t b = __builtin_convertvector(v, bf16x2_t); return __builtin_bit_cast(unsigned, b); }
; __device__ __forceinline__ void norm_rows(const XSrc src, const float* gain, bf16_t* dbf, float* df32) {
;     ...
;         const float rs = 1.0f / sqrtf(ss * (1.0f / DM) + 1e-6f), rt = 1.0f / sqrtf(st * (1.0f / DM) + 1e-6f);
; #pragma unroll
;         for (int i = 0; i < 8; ++i) {
;             const f32x4 gn = *(const f32x4*)(gain + i * 256 + lane * 4);
;             const f32x4 y = v[i] * rs * gn, y2 = u[i] * rt * gn;
;             if (dbf) { u32x2 w; w.x = cvt_pk_bf16(y[0], y[1]); w.y = cvt_pk_bf16(y[2], y[3]); *(u32x2*)(dbf + (size_t)row * DM + i * 256 + lane * 4) = w;
;                        if (row2 != row) { w.x = cvt_pk_bf16(y2[0], y2[1]); w.y = cvt_pk_bf16(y2[2], y2[3]); *(u32x2*)(dbf + (size_t)row2 * DM + i * 256 + lane * 4) = w; } }
;             if (df32) { *(f32x4*)(df32 + (size_t)row * DM + i * 256 + lane * 4) = y; if (row2 != row) *(f32x4*)(df32 + (size_t)row2 * DM + i * 256 + lane * 4) = y2; }
	v_add_f32_e32 v88, v88, v91
	ds_bpermute_b32 v91, v96, v88
	v_add_u32_e32 v92, -1, v90
	v_fma_f32 v93, -v92, v90, v89
	v_cmp_ge_f32_e64 s[4:5], 0, v93
	v_add_u32_e32 v93, 1, v90
	s_waitcnt lgkmcnt(0)
	v_add_f32_e32 v88, v88, v91
	ds_bpermute_b32 v91, v97, v88
	v_cndmask_b32_e64 v92, v90, v92, s[4:5]
	v_fma_f32 v90, -v93, v90, v89
	v_cmp_lt_f32_e64 s[4:5], 0, v90
	s_waitcnt lgkmcnt(0)
	v_add_f32_e32 v88, v88, v91
	v_cndmask_b32_e64 v90, v92, v93, s[4:5]
	v_mul_f32_e32 v92, 0x37800000, v90
	v_cndmask_b32_e32 v90, v90, v92, vcc
	v_cmp_class_f32_e32 vcc, v89, v105
	s_nop 1
	v_cndmask_b32_e32 v89, v90, v89, vcc
	ds_bpermute_b32 v90, v98, v88
	v_div_scale_f32 v91, s[4:5], v89, v89, 1.0
	v_rcp_f32_e32 v92, v91
	s_waitcnt lgkmcnt(0)
	v_add_f32_e32 v88, v88, v90
	ds_bpermute_b32 v90, v99, v88
	v_fma_f32 v93, -v91, v92, 1.0
	v_fmac_f32_e32 v92, v93, v92
	v_div_scale_f32 v93, vcc, 1.0, v89, 1.0
	s_waitcnt lgkmcnt(0)
	v_add_f32_e32 v88, v88, v90
	v_fmamk_f32 v88, v88, 0x3a000000, v104
	v_mul_f32_e32 v90, 0x4f800000, v88
	v_cmp_gt_f32_e64 s[4:5], s15, v88
	v_mul_f32_e32 v107, v93, v92
	v_fma_f32 v108, -v91, v107, v93
	v_cndmask_b32_e64 v88, v88, v90, s[4:5]
	v_sqrt_f32_e32 v90, v88
	v_fmac_f32_e32 v107, v108, v92
	v_fma_f32 v91, -v91, v107, v93
	v_div_fmas_f32 v91, v91, v92, v107
	v_add_u32_e32 v108, -1, v90
	v_fma_f32 v109, -v108, v90, v88
	v_cmp_ge_f32_e64 s[6:7], 0, v109
	v_add_u32_e32 v109, 1, v90
	s_nop 0
	v_cndmask_b32_e64 v108, v90, v108, s[6:7]
	v_fma_f32 v90, -v109, v90, v88
	v_cmp_lt_f32_e64 s[6:7], 0, v90
	s_nop 1
	v_cndmask_b32_e64 v90, v108, v109, s[6:7]
	v_mul_f32_e32 v108, 0x37800000, v90
	v_cndmask_b32_e64 v90, v90, v108, s[4:5]
	v_cmp_class_f32_e64 s[4:5], v88, v105
	s_nop 1
	v_cndmask_b32_e64 v88, v90, v88, s[4:5]
	v_div_scale_f32 v90, s[4:5], v88, v88, 1.0
	v_rcp_f32_e32 v108, v90
	s_nop 0
	v_fma_f32 v92, -v90, v108, 1.0
	v_fmac_f32_e32 v108, v92, v108
	v_div_scale_f32 v92, vcc, 1.0, v88, 1.0
	v_mul_f32_e32 v93, v92, v108
	v_fma_f32 v107, -v90, v93, v92
	v_fmac_f32_e32 v93, v107, v108
	v_fma_f32 v90, -v90, v93, v92
	v_div_fmas_f32 v107, v90, v108, v93
	v_div_fixup_f32 v90, v91, v89, 1.0
	v_pk_mul_f32 v[22:23], v[22:23], v[90:91] op_sel_hi:[1,0]
	v_pk_mul_f32 v[24:25], v[24:25], v[90:91] op_sel_hi:[1,0]
	v_pk_mul_f32 v[22:23], v[196:197], v[22:23]
	v_pk_mul_f32 v[24:25], v[198:199], v[24:25]
	v_cvt_pk_bf16_f32 v22, v22, v23
	v_cvt_pk_bf16_f32 v23, v24, v25
	v_lshlrev_b64 v[24:25], 12, v[84:85]
	v_lshl_add_u64 v[92:93], v[74:75], 0, v[24:25]
	global_store_dwordx2 v[92:93], v[22:23], off
	v_div_fixup_f32 v88, v107, v88, 1.0
	v_lshlrev_b64 v[22:23], 12, v[86:87]
	v_cmp_ne_u32_e32 vcc, v84, v86
	v_mov_b32_e32 v89, v88
	v_lshl_add_u64 v[84:85], v[74:75], 0, v[22:23]
	s_and_saveexec_b64 s[4:5], vcc
	s_cbranch_execz .LBB0_145
	v_mov_b32_e32 v22, v88
	v_mov_b32_e32 v23, v88
	v_pk_mul_f32 v[22:23], v[64:65], v[22:23]
	v_pk_mul_f32 v[24:25], v[62:63], v[88:89]
	v_pk_mul_f32 v[22:23], v[198:199], v[22:23]
	v_pk_mul_f32 v[24:25], v[196:197], v[24:25]
	s_nop 0
	v_cvt_pk_bf16_f32 v24, v24, v25
	v_cvt_pk_bf16_f32 v25, v22, v23
	global_store_dwordx2 v[84:85], v[24:25], off
.LBB0_145:
	s_or_b64 exec, exec, s[4:5]
	v_mov_b32_e32 v91, v90
	v_mov_b32_e32 v62, v90
	v_mov_b32_e32 v63, v90
	v_pk_mul_f32 v[52:53], v[52:53], v[62:63]
	v_pk_mul_f32 v[50:51], v[50:51], v[90:91]
	v_pk_mul_f32 v[52:53], v[52:53], v[202:203]
	v_pk_mul_f32 v[50:51], v[50:51], v[200:201]
	s_nop 0
	v_cvt_pk_bf16_f32 v50, v50, v51
	v_cvt_pk_bf16_f32 v51, v52, v53
	global_store_dwordx2 v[92:93], v[50:51], off offset:512
	s_and_saveexec_b64 s[4:5], vcc
	s_cbranch_execz .LBB0_147
	v_mov_b32_e32 v50, v88
	v_mov_b32_e32 v51, v88
	v_pk_mul_f32 v[50:51], v[60:61], v[50:51]
	v_pk_mul_f32 v[52:53], v[58:59], v[88:89]
	v_pk_mul_f32 v[24:25], v[50:51], v[202:203]
	v_pk_mul_f32 v[22:23], v[52:53], v[200:201]
	s_nop 0
	v_cvt_pk_bf16_f32 v22, v22, v23
	v_cvt_pk_bf16_f32 v23, v24, v25
	global_store_dwordx2 v[84:85], v[22:23], off offset:512
; __device__ __forceinline__ unsigned cvt_pk_bf16(float lo, float hi) { const f32x2 v = {lo, hi}; const bf16x2_t b = __builtin_convertvector(v, bf16x2_t); return __builtin_bit_cast(unsigned, b); }
; __device__ __forceinline__ void norm_rows(const XSrc src, const float* gain, bf16_t* dbf, float* df32) {
;     ...
; #pragma unroll
;         for (int i = 0; i < 8; ++i) {
;             const f32x4 gn = *(const f32x4*)(gain + i * 256 + lane * 4);
;             const f32x4 y = v[i] * rs * gn, y2 = u[i] * rt * gn;
;             if (dbf) { u32x2 w; w.x = cvt_pk_bf16(y[0], y[1]); w.y = cvt_pk_bf16(y[2], y[3]); *(u32x2*)(dbf + (size_t)row * DM + i * 256 + lane * 4) = w;
;                        if (row2 != row) { w.x = cvt_pk_bf16(y2[0], y2[1]); w.y = cvt_pk_bf16(y2[2], y2[3]); *(u32x2*)(dbf + (size_t)row2 * DM + i * 256 + lane * 4) = w; } }
;             if (df32) { *(f32x4*)(df32 + (size_t)row * DM + i * 256 + lane * 4) = y; if (row2 != row) *(f32x4*)(df32 + (size_t)row2 * DM + i * 256 + lane * 4) = y2; }
;         }
.LBB0_147:
	s_or_b64 exec, exec, s[4:5]
	v_pk_mul_f32 v[48:49], v[48:49], v[62:63]
	v_pk_mul_f32 v[46:47], v[46:47], v[90:91]
	v_pk_mul_f32 v[48:49], v[48:49], v[206:207]
	v_pk_mul_f32 v[46:47], v[46:47], v[204:205]
	s_nop 0
	v_cvt_pk_bf16_f32 v46, v46, v47
	v_cvt_pk_bf16_f32 v47, v48, v49
	global_store_dwordx2 v[92:93], v[46:47], off offset:1024
	s_and_saveexec_b64 s[4:5], vcc
	s_cbranch_execz .LBB0_149
	v_mov_b32_e32 v46, v88
	v_mov_b32_e32 v47, v88
	v_pk_mul_f32 v[46:47], v[56:57], v[46:47]
	v_pk_mul_f32 v[48:49], v[54:55], v[88:89]
	v_pk_mul_f32 v[24:25], v[46:47], v[206:207]
	v_pk_mul_f32 v[22:23], v[48:49], v[204:205]
	s_nop 0
	v_cvt_pk_bf16_f32 v22, v22, v23
	v_cvt_pk_bf16_f32 v23, v24, v25
	global_store_dwordx2 v[84:85], v[22:23], off offset:1024
.LBB0_149:
	s_or_b64 exec, exec, s[4:5]
	v_mov_b32_e32 v46, v90
	v_mov_b32_e32 v47, v90
	v_pk_mul_f32 v[34:35], v[34:35], v[90:91]
	v_pk_mul_f32 v[36:37], v[36:37], v[46:47]
	v_pk_mul_f32 v[34:35], v[34:35], v[208:209]
	v_pk_mul_f32 v[36:37], v[36:37], v[210:211]
	v_cvt_pk_bf16_f32 v34, v34, v35
	v_cvt_pk_bf16_f32 v35, v36, v37
	global_store_dwordx2 v[92:93], v[34:35], off offset:1536
	s_and_saveexec_b64 s[4:5], vcc
	s_cbranch_execz .LBB0_151
	v_mov_b32_e32 v34, v88
	v_mov_b32_e32 v35, v88
	v_pk_mul_f32 v[34:35], v[44:45], v[34:35]
	v_pk_mul_f32 v[36:37], v[42:43], v[88:89]
	v_pk_mul_f32 v[24:25], v[34:35], v[210:211]
	v_pk_mul_f32 v[22:23], v[36:37], v[208:209]
	s_nop 0
	v_cvt_pk_bf16_f32 v22, v22, v23
	v_cvt_pk_bf16_f32 v23, v24, v25
	global_store_dwordx2 v[84:85], v[22:23], off offset:1536
.LBB0_151:
	s_or_b64 exec, exec, s[4:5]
	v_pk_mul_f32 v[32:33], v[32:33], v[46:47]
	v_pk_mul_f32 v[30:31], v[30:31], v[90:91]
	v_pk_mul_f32 v[32:33], v[32:33], v[214:215]
	v_pk_mul_f32 v[30:31], v[30:31], v[212:213]
	s_nop 0
	v_cvt_pk_bf16_f32 v30, v30, v31
	v_cvt_pk_bf16_f32 v31, v32, v33
	global_store_dwordx2 v[92:93], v[30:31], off offset:2048
	s_and_saveexec_b64 s[4:5], vcc
	s_cbranch_execz .LBB0_153
	v_mov_b32_e32 v30, v88
	v_mov_b32_e32 v31, v88
	v_pk_mul_f32 v[30:31], v[40:41], v[30:31]
	v_pk_mul_f32 v[32:33], v[38:39], v[88:89]
	v_pk_mul_f32 v[24:25], v[30:31], v[214:215]
	v_pk_mul_f32 v[22:23], v[32:33], v[212:213]
	s_nop 0
	v_cvt_pk_bf16_f32 v22, v22, v23
	v_cvt_pk_bf16_f32 v23, v24, v25
	global_store_dwordx2 v[84:85], v[22:23], off offset:2048
.LBB0_153:
	s_or_b64 exec, exec, s[4:5]
	v_mov_b32_e32 v30, v90
	v_mov_b32_e32 v31, v90
	v_pk_mul_f32 v[18:19], v[18:19], v[90:91]
	v_pk_mul_f32 v[20:21], v[20:21], v[30:31]
	v_pk_mul_f32 v[18:19], v[18:19], v[216:217]
	v_pk_mul_f32 v[20:21], v[20:21], v[218:219]
	v_cvt_pk_bf16_f32 v18, v18, v19
	v_cvt_pk_bf16_f32 v19, v20, v21
	global_store_dwordx2 v[92:93], v[18:19], off offset:2560
	s_and_saveexec_b64 s[4:5], vcc
	s_cbranch_execz .LBB0_155
	v_mov_b32_e32 v18, v88
	v_mov_b32_e32 v19, v88
	v_pk_mul_f32 v[18:19], v[28:29], v[18:19]
	v_pk_mul_f32 v[20:21], v[26:27], v[88:89]
	v_pk_mul_f32 v[18:19], v[18:19], v[218:219]
	v_pk_mul_f32 v[20:21], v[20:21], v[216:217]
	s_nop 0
	v_cvt_pk_bf16_f32 v20, v20, v21
	v_cvt_pk_bf16_f32 v21, v18, v19
	global_store_dwordx2 v[84:85], v[20:21], off offset:2560
.LBB0_155:
	s_or_b64 exec, exec, s[4:5]
	v_pk_mul_f32 v[12:13], v[12:13], v[30:31]
	v_pk_mul_f32 v[10:11], v[10:11], v[90:91]
	v_pk_mul_f32 v[12:13], v[12:13], v[222:223]
	v_pk_mul_f32 v[10:11], v[10:11], v[220:221]
	s_nop 0
	v_cvt_pk_bf16_f32 v10, v10, v11
	v_cvt_pk_bf16_f32 v11, v12, v13
	global_store_dwordx2 v[92:93], v[10:11], off offset:3072
	s_and_saveexec_b64 s[4:5], vcc
	s_cbranch_execz .LBB0_157
	v_mov_b32_e32 v10, v88
	v_mov_b32_e32 v11, v88
	v_pk_mul_f32 v[10:11], v[16:17], v[10:11]
	v_pk_mul_f32 v[12:13], v[14:15], v[88:89]
	v_pk_mul_f32 v[10:11], v[10:11], v[222:223]
	v_pk_mul_f32 v[12:13], v[12:13], v[220:221]
	s_nop 0
	v_cvt_pk_bf16_f32 v12, v12, v13
	v_cvt_pk_bf16_f32 v13, v10, v11
	global_store_dwordx2 v[84:85], v[12:13], off offset:3072
.LBB0_157:
	s_or_b64 exec, exec, s[4:5]
	v_mov_b32_e32 v14, v90
	v_mov_b32_e32 v15, v90
	v_pk_mul_f32 v[2:3], v[2:3], v[90:91]
	v_pk_mul_f32 v[4:5], v[4:5], v[14:15]
	v_pk_mul_f32 v[2:3], v[2:3], v[224:225]
	v_pk_mul_f32 v[4:5], v[4:5], v[226:227]
	v_cvt_pk_bf16_f32 v2, v2, v3
	v_cvt_pk_bf16_f32 v3, v4, v5
	global_store_dwordx2 v[92:93], v[2:3], off offset:3584
	s_and_saveexec_b64 s[4:5], vcc
	s_cbranch_execz .LBB0_142
	v_mov_b32_e32 v2, v88
	v_mov_b32_e32 v3, v88
	v_pk_mul_f32 v[2:3], v[8:9], v[2:3]
	v_pk_mul_f32 v[4:5], v[6:7], v[88:89]
	v_pk_mul_f32 v[2:3], v[2:3], v[226:227]
	v_pk_mul_f32 v[4:5], v[4:5], v[224:225]
	s_nop 0
	v_cvt_pk_bf16_f32 v4, v4, v5
	v_cvt_pk_bf16_f32 v5, v2, v3
	global_store_dwordx2 v[84:85], v[4:5], off offset:3584
	s_branch .LBB0_142

; #define LAS __attribute__((address_space(3)))
; __device__ __forceinline__ int fresh_tid() { int t = threadIdx.x; asm volatile("" : "+v"(t)); return t; }
; __device__ __forceinline__ int fresh_bid() { int t = blockIdx.x; asm volatile("" : "+s"(t)); return t; }
; __device__ __forceinline__ void skinny_resid(const bf16_t* A, int lda, const bf16_t* Wt, int ldb, int K, const XSrc res, float* out, LAS unsigned char* lds) {
;     const int tid = fresh_tid(), w = tid >> 6, lane = tid & 63, r = lane & 15, q = lane >> 4;
;     LAS float* red = (LAS float*)lds;
;     for (int piece = fresh_bid(); piece < 256; piece += gridDim.x) {
;         const int rh = piece & 1, cg = piece >> 1;
;         const bf16_t* ap = A + (size_t)(NPROMPT + rh * 64 + r) * lda + q * 8;
;         const bf16_t* bp = Wt + (size_t)(cg * 16 + r) * ldb + q * 8;
;         const int ksper = K / 256, k0 = w * ksper * 32;
;         f32x4 acc[4];
; #pragma unroll
;         for (int mt = 0; mt < 4; ++mt) acc[mt] = (f32x4){0.f, 0.f, 0.f, 0.f};
; #pragma unroll 4
;         for (int ks = 0; ks < ksper; ++ks) {
;             const int k = k0 + ks * 32;
;             const bf16x8 b = *(const bf16x8*)(bp + k);
;             bf16x8 a[4];
; #pragma unroll
;             for (int mt = 0; mt < 4; ++mt) a[mt] = *(const bf16x8*)(ap + (size_t)mt * 16 * lda + k);
; #pragma unroll
;             for (int mt = 0; mt < 4; ++mt) acc[mt] = __builtin_amdgcn_mfma_f32_16x16x32_bf16(a[mt], b, acc[mt], 0, 0, 0);
;         }
; #pragma unroll
;         for (int mt = 0; mt < 4; ++mt) *(LAS f32x4*)(red + w * 1024 + (mt * 64 + lane) * 4) = acc[mt];
;         __syncthreads();
; #pragma unroll
;         for (int h = 0; h < 2; ++h) {
;             const int e = tid + h * 512;
;             float sum = 0.f;
; #pragma unroll
;             for (int ww = 0; ww < 8; ++ww) sum += red[ww * 1024 + e];
;             const int mt = e >> 8, ln = (e >> 2) & 63, j = e & 3;
;             const int row = NPROMPT + rh * 64 + mt * 16 + (ln >> 4) * 4 + j, col = cg * 16 + (ln & 15);
;             out[(size_t)row * DM + col] = res.row(row)[col] + sum;
;         }
;         __syncthreads();
;     }
.LBB0_1414:
	v_lshl_add_u64 v[54:55], v[22:23], 0, s[4:5]
	s_mov_b32 s9, 0x2b220000
	v_add_co_u32_e32 v26, vcc, s9, v54
	s_mov_b32 s9, 0x2b230000
	s_nop 0
	v_addc_co_u32_e32 v27, vcc, 0, v55, vcc
	v_add_co_u32_e32 v28, vcc, s9, v54
	s_mov_b32 s9, 0x2b240000
	s_nop 0
	v_addc_co_u32_e32 v29, vcc, 0, v55, vcc
	v_add_co_u32_e32 v60, vcc, s9, v54
	s_mov_b32 s9, 0x2b250000
	s_nop 0
	v_addc_co_u32_e32 v61, vcc, 0, v55, vcc
	v_add_co_u32_e32 v62, vcc, s9, v54
	v_lshl_add_u64 v[58:59], v[24:25], 0, s[4:5]
	s_nop 0
	v_addc_co_u32_e32 v63, vcc, 0, v55, vcc
	global_load_dwordx4 v[102:105], v[58:59], off offset:-128
	global_load_dwordx4 v[106:109], v[26:27], off
	global_load_dwordx4 v[110:113], v[28:29], off
	global_load_dwordx4 v[114:117], v[60:61], off
	global_load_dwordx4 v[118:121], v[62:63], off
	global_load_dwordx4 v[156:159], v[58:59], off offset:-64
	global_load_dwordx4 v[160:163], v[26:27], off offset:64
	global_load_dwordx4 v[164:167], v[28:29], off offset:64
	global_load_dwordx4 v[168:171], v[60:61], off offset:64
	global_load_dwordx4 v[172:175], v[62:63], off offset:64
	global_load_dwordx4 v[194:197], v[58:59], off
	global_load_dwordx4 v[198:201], v[26:27], off offset:128
	global_load_dwordx4 v[202:205], v[28:29], off offset:128
	global_load_dwordx4 v[206:209], v[60:61], off offset:128
	global_load_dwordx4 v[210:213], v[62:63], off offset:128
	global_load_dwordx4 v[214:217], v[58:59], off offset:64
	global_load_dwordx4 v[218:221], v[26:27], off offset:192
	global_load_dwordx4 v[222:225], v[28:29], off offset:192
	global_load_dwordx4 v[226:229], v[60:61], off offset:192
	global_load_dwordx4 v[230:233], v[62:63], off offset:192
	s_add_u32 s4, s4, 0x100
	s_addc_u32 s5, s5, 0
	s_cmpk_eq_i32 s4, 0x200
	s_waitcnt vmcnt(15)
	v_mfma_f32_16x16x32_bf16 v[6:9], v[106:109], v[102:105], v[6:9]
	v_mfma_f32_16x16x32_bf16 v[10:13], v[110:113], v[102:105], v[10:13]
	v_mfma_f32_16x16x32_bf16 v[14:17], v[114:117], v[102:105], v[14:17]
	v_mfma_f32_16x16x32_bf16 v[2:5], v[118:121], v[102:105], v[2:5]
	s_waitcnt vmcnt(10)
	v_mfma_f32_16x16x32_bf16 v[6:9], v[160:163], v[156:159], v[6:9]
	v_mfma_f32_16x16x32_bf16 v[10:13], v[164:167], v[156:159], v[10:13]
	v_mfma_f32_16x16x32_bf16 v[14:17], v[168:171], v[156:159], v[14:17]
	v_mfma_f32_16x16x32_bf16 v[2:5], v[172:175], v[156:159], v[2:5]
	s_waitcnt vmcnt(5)
	v_mfma_f32_16x16x32_bf16 v[6:9], v[198:201], v[194:197], v[6:9]
	v_mfma_f32_16x16x32_bf16 v[10:13], v[202:205], v[194:197], v[10:13]
	v_mfma_f32_16x16x32_bf16 v[14:17], v[206:209], v[194:197], v[14:17]
	v_mfma_f32_16x16x32_bf16 v[2:5], v[210:213], v[194:197], v[2:5]
	s_waitcnt vmcnt(0)
	v_mfma_f32_16x16x32_bf16 v[6:9], v[218:221], v[214:217], v[6:9]
	v_mfma_f32_16x16x32_bf16 v[10:13], v[222:225], v[214:217], v[10:13]
	v_mfma_f32_16x16x32_bf16 v[14:17], v[226:229], v[214:217], v[14:17]
	v_mfma_f32_16x16x32_bf16 v[2:5], v[230:233], v[214:217], v[2:5]
	s_cbranch_scc0 .LBB0_1414
	s_nop 3
	ds_write_b128 v31, v[6:9]
	ds_write_b128 v31, v[10:13] offset:1024
	ds_write_b128 v31, v[14:17] offset:2048
	ds_write_b128 v31, v[2:5] offset:3072
	s_waitcnt lgkmcnt(0)
	s_barrier
	ds_read2st64_b32 v[6:7], v34 offset1:8
	ds_read2st64_b32 v[8:9], v34 offset0:16 offset1:24
	ds_read2st64_b32 v[10:11], v34 offset0:32 offset1:40
	ds_read2st64_b32 v[12:13], v34 offset0:48 offset1:56
	ds_read2st64_b32 v[14:15], v34 offset0:64 offset1:72
	s_lshl_b32 s4, s6, 6
	s_waitcnt lgkmcnt(4)
	v_add_f32_e32 v6, 0, v6
	ds_read2st64_b32 v[16:17], v34 offset0:80 offset1:88
	v_and_or_b32 v0, s4, 64, v32
	s_waitcnt lgkmcnt(4)
	v_add_f32_e32 v6, v6, v8
	v_or_b32_e32 v0, 0x2000, v0
	s_waitcnt lgkmcnt(3)
	v_add_f32_e32 v6, v6, v10
	s_waitcnt lgkmcnt(2)
	v_add_f32_e32 v6, v6, v12
	v_add_u32_e32 v26, v0, v35
	s_lshl_b32 s5, s6, 3
	s_waitcnt lgkmcnt(1)
	v_add_f32_e32 v6, v6, v14
	v_cmp_gt_i32_e32 vcc, s34, v26
	v_subrev_u32_e32 v8, s34, v26
	v_ashrrev_i32_e32 v27, 31, v26
	v_and_or_b32 v2, s5, -16, v33
	s_waitcnt lgkmcnt(0)
	v_add_f32_e32 v6, v6, v16
	v_cndmask_b32_e32 v29, 0, v27, vcc
	v_cndmask_b32_e32 v28, v8, v26, vcc
	v_mov_b32_e32 v10, s15
	v_mov_b32_e32 v12, s13
	v_mov_b32_e32 v14, s14
	v_mov_b32_e32 v16, s12
	v_ashrrev_i32_e32 v3, 31, v2
	v_cndmask_b32_e32 v39, v10, v12, vcc
	v_cndmask_b32_e32 v38, v14, v16, vcc
	v_lshlrev_b64 v[28:29], 13, v[28:29]
	v_lshlrev_b64 v[4:5], 2, v[2:3]
	v_lshl_add_u64 v[28:29], v[38:39], 0, v[28:29]
	v_lshl_add_u64 v[28:29], v[28:29], 0, v[4:5]
	global_load_dword v8, v[28:29], off
	ds_read2st64_b32 v[22:23], v34 offset0:96 offset1:104
	ds_read2st64_b32 v[24:25], v34 offset0:112 offset1:120
	v_lshl_add_u64 v[2:3], s[0:1], 0, v[4:5]
	v_lshlrev_b64 v[26:27], 13, v[26:27]
	v_lshl_add_u64 v[26:27], v[2:3], 0, v[26:27]
	s_waitcnt lgkmcnt(1)
	v_add_f32_e32 v6, v6, v22
	s_waitcnt lgkmcnt(0)
	v_add_f32_e32 v6, v6, v24
	s_add_i32 s6, s6, s74
	s_add_i32 s7, s7, s55
	s_add_i32 s8, s8, s97
	s_cmpk_gt_i32 s6, 0xff
	s_waitcnt vmcnt(0)
	v_add_f32_e32 v6, v6, v8
	global_store_dword v[26:27], v6, off
	v_add_f32_e32 v6, 0, v7
	v_add_f32_e32 v6, v6, v9
	v_add_f32_e32 v6, v6, v11
	v_add_f32_e32 v6, v6, v13
	v_add_f32_e32 v6, v6, v15
	v_add_f32_e32 v6, v6, v17
	v_add_f32_e32 v6, v6, v23
	v_add_f32_e32 v13, v6, v25
	v_add_u32_e32 v6, v0, v36
	v_cmp_gt_i32_e32 vcc, s34, v6
	v_subrev_u32_e32 v0, s34, v6
	v_ashrrev_i32_e32 v7, 31, v6
	v_cndmask_b32_e32 v9, 0, v7, vcc
	v_cndmask_b32_e32 v8, v0, v6, vcc
	v_cndmask_b32_e32 v11, v10, v12, vcc
	v_cndmask_b32_e32 v10, v14, v16, vcc
	v_lshlrev_b64 v[8:9], 13, v[8:9]
	v_lshl_add_u64 v[8:9], v[10:11], 0, v[8:9]
	v_lshl_add_u64 v[4:5], v[8:9], 0, v[4:5]
	global_load_dword v0, v[4:5], off
	v_lshlrev_b64 v[4:5], 13, v[6:7]
	v_lshl_add_u64 v[2:3], v[2:3], 0, v[4:5]
	s_waitcnt vmcnt(0)
	v_add_f32_e32 v0, v13, v0
	global_store_dword v[2:3], v0, off
	s_barrier
	s_cbranch_scc0 .LBB0_1413

; __device__ __forceinline__ ParamsK fresh_params() { unsigned long long a = (unsigned long long)__builtin_amdgcn_kernarg_segment_ptr(); asm volatile("" : "+s"(a)); return (ParamsK)a; }
; __device__ __forceinline__ int fresh_tid() { int t = threadIdx.x; asm volatile("" : "+v"(t)); return t; }
; __device__ __forceinline__ int fresh_bid() { int t = blockIdx.x; asm volatile("" : "+s"(t)); return t; }
; __device__ __forceinline__ void norm_rows(const XSrc src, const float* gain, bf16_t* dbf, float* df32) {
;     const int lane = fresh_tid() & 63, gw = fresh_bid() * 8 + (fresh_tid() >> 6), nw = gridDim.x * 8;
;     for (int row = gw; row < MROWS; row += 2 * nw) {
;         const int row2 = row + nw < MROWS ? row + nw : row;
;         const float* xp = src.row(row); const float* xq = src.row(row2);
;         f32x4 v[8], u[8]; float ss = 0.f, st = 0.f;
; #pragma unroll
;         for (int i = 0; i < 8; ++i) { v[i] = *(const f32x4*)(xp + i * 256 + lane * 4); u[i] = *(const f32x4*)(xq + i * 256 + lane * 4); }
; #pragma unroll
;         for (int i = 0; i < 8; ++i) { ss += v[i][0] * v[i][0] + v[i][1] * v[i][1] + v[i][2] * v[i][2] + v[i][3] * v[i][3]; st += u[i][0] * u[i][0] + u[i][1] * u[i][1] + u[i][2] * u[i][2] + u[i][3] * u[i][3]; }
; #pragma unroll
;         for (int o = 32; o > 0; o >>= 1) { ss += __shfl_xor(ss, o); st += __shfl_xor(st, o); }
;         const float rs = 1.0f / sqrtf(ss * (1.0f / DM) + 1e-6f), rt = 1.0f / sqrtf(st * (1.0f / DM) + 1e-6f);
; #pragma unroll
;         for (int i = 0; i < 8; ++i) {
;             const f32x4 gn = *(const f32x4*)(gain + i * 256 + lane * 4);
; __global__ void __launch_bounds__(512) hybrid_fwd(Params p_unused) {
;     ...
;         { ParamsK p = fresh_params(); const float* X1 = (const float*)(p->ws + WS_X1); XSrc s; s.a = X1; s.b = X1; s.split = MP; s.valid = MP; for (int rep = 0; rep < REP_NORM; ++rep) norm_rows(s, p->in[25] + l * DM, (bf16_t*)(p->ws + WS_XN), nullptr); }
.LBB0_1469:
	s_or_b64 exec, exec, s[0:1]
	s_mov_b64 s[4:5], s[84:85]
	v_mov_b32_e32 v0, v176
	s_mov_b32 s0, s94
	s_waitcnt lgkmcnt(0)
	v_mov_b32_e32 v2, v176
	s_barrier
	s_nop 0
	v_ashrrev_i32_e32 v2, 6, v2
	v_lshl_add_u32 v66, s0, 3, v2
	s_movk_i32 s0, 0x2080
	v_cmp_gt_i32_e32 vcc, s0, v66
	s_and_saveexec_b64 s[0:1], vcc
	s_cbranch_execz .LBB0_1488
	s_load_dwordx2 s[6:7], s[4:5], 0xc8
	s_nop 0
	s_load_dwordx2 s[4:5], s[4:5], 0xf8
	v_readlane_b32 s8, v252, 19
	v_readlane_b32 s9, v252, 20
	s_lshl_b32 s52, s8, 11
	v_lshlrev_b32_e32 v0, 2, v0
	s_lshl_b64 s[8:9], s[52:53], 2
	s_waitcnt lgkmcnt(0)
	s_add_u32 s6, s6, s8
	v_and_b32_e32 v2, 0xfc, v0
	v_and_b32_e32 v0, 64, v181
	s_addc_u32 s7, s7, s9
	v_add_u32_e32 v4, 64, v0
	v_lshlrev_b32_e32 v0, 2, v2
	v_lshlrev_b32_e32 v2, 1, v2
	v_mov_b32_e32 v3, v1
	v_lshl_add_u64 v[70:71], s[6:7], 0, v[0:1]
	v_lshl_add_u64 v[2:3], s[4:5], 0, v[2:3]
	s_mov_b64 s[6:7], 0x12200000
	v_lshl_add_u64 v[72:73], v[2:3], 0, s[6:7]
	v_xor_b32_e32 v2, 32, v181
	v_cmp_lt_i32_e32 vcc, v2, v4
	s_mov_b64 s[6:7], 0x1000
	v_lshl_add_u64 v[74:75], v[70:71], 0, s[6:7]
	v_cndmask_b32_e32 v2, v181, v2, vcc
	v_lshlrev_b32_e32 v92, 2, v2
	v_xor_b32_e32 v2, 16, v181
	v_cmp_lt_i32_e32 vcc, v2, v4
	s_mov_b64 s[6:7], 0x1400
	v_lshl_add_u64 v[76:77], v[70:71], 0, s[6:7]
	v_cndmask_b32_e32 v2, v181, v2, vcc
	v_lshlrev_b32_e32 v93, 2, v2
	v_xor_b32_e32 v2, 8, v181
	v_cmp_lt_i32_e32 vcc, v2, v4
	s_mov_b64 s[6:7], 0x1800
	v_lshl_add_u64 v[78:79], v[70:71], 0, s[6:7]
	v_cndmask_b32_e32 v2, v181, v2, vcc
	v_lshlrev_b32_e32 v94, 2, v2
	v_xor_b32_e32 v2, 4, v181
	v_cmp_lt_i32_e32 vcc, v2, v4
	s_mov_b64 s[6:7], 0x1c00
	v_lshl_add_u64 v[80:81], v[70:71], 0, s[6:7]
	v_cndmask_b32_e32 v2, v181, v2, vcc
	v_lshlrev_b32_e32 v95, 2, v2
	v_xor_b32_e32 v2, 2, v181
	v_cmp_lt_i32_e32 vcc, v2, v4
	s_mov_b64 s[6:7], 0
	s_nop 0
	v_cndmask_b32_e32 v2, v181, v2, vcc
	v_lshlrev_b32_e32 v96, 2, v2
	v_xor_b32_e32 v2, 1, v181
	v_cmp_lt_i32_e32 vcc, v2, v4
	s_nop 1
	v_cndmask_b32_e32 v2, v181, v2, vcc
	v_lshlrev_b32_e32 v97, 2, v2
	v_lshl_add_u64 v[2:3], s[4:5], 0, v[0:1]
	s_mov_b64 s[4:5], 0x2d320000
	v_lshl_add_u64 v[82:83], v[2:3], 0, s[4:5]
	global_load_dwordx4 v[196:199], v[70:71], off
	global_load_dwordx4 v[200:203], v[70:71], off offset:1024
	global_load_dwordx4 v[204:207], v[70:71], off offset:2048
	global_load_dwordx4 v[208:211], v[70:71], off offset:3072
	global_load_dwordx4 v[212:215], v[74:75], off
	global_load_dwordx4 v[216:219], v[76:77], off
	global_load_dwordx4 v[220:223], v[78:79], off
	global_load_dwordx4 v[224:227], v[80:81], off
	s_branch .LBB0_1472

; __device__ __forceinline__ void norm_rows(const XSrc src, const float* gain, bf16_t* dbf, float* df32) {
;     ...
;     for (int row = gw; row < MROWS; row += 2 * nw) {
;         const int row2 = row + nw < MROWS ? row + nw : row;
;         const float* xp = src.row(row); const float* xq = src.row(row2);
;         f32x4 v[8], u[8]; float ss = 0.f, st = 0.f;
; #pragma unroll
;         for (int i = 0; i < 8; ++i) { v[i] = *(const f32x4*)(xp + i * 256 + lane * 4); u[i] = *(const f32x4*)(xq + i * 256 + lane * 4); }
; #pragma unroll
;         for (int i = 0; i < 8; ++i) { ss += v[i][0] * v[i][0] + v[i][1] * v[i][1] + v[i][2] * v[i][2] + v[i][3] * v[i][3]; st += u[i][0] * u[i][0] + u[i][1] * u[i][1] + u[i][2] * u[i][2] + u[i][3] * u[i][3]; }
; #pragma unroll
;         for (int o = 32; o > 0; o >>= 1) { ss += __shfl_xor(ss, o); st += __shfl_xor(st, o); }
.LBB0_1472:
	v_add_u32_e32 v0, s97, v66
	s_movk_i32 s2, 0x2080
	v_cmp_gt_i32_e32 vcc, s2, v0
	v_ashrrev_i32_e32 v67, 31, v66
	v_lshlrev_b64 v[2:3], 13, v[66:67]
	v_cndmask_b32_e32 v68, v66, v0, vcc
	v_cmp_gt_i32_e32 vcc, s38, v68
	v_add_u32_e32 v4, 0xffffdf00, v68
	v_ashrrev_i32_e32 v69, 31, v68
	v_cndmask_b32_e32 v5, 0, v69, vcc
	v_cndmask_b32_e32 v4, v4, v68, vcc
	v_lshlrev_b64 v[4:5], 13, v[4:5]
	v_lshl_add_u64 v[2:3], v[82:83], 0, v[2:3]
	v_lshl_add_u64 v[4:5], v[82:83], 0, v[4:5]
	global_load_dwordx4 v[62:65], v[2:3], off
	global_load_dwordx4 v[58:61], v[4:5], off
	global_load_dwordx4 v[54:57], v[2:3], off offset:1024
	global_load_dwordx4 v[50:53], v[4:5], off offset:1024
	global_load_dwordx4 v[46:49], v[2:3], off offset:2048
	global_load_dwordx4 v[42:45], v[4:5], off offset:2048
	global_load_dwordx4 v[38:41], v[2:3], off offset:3072
	global_load_dwordx4 v[30:33], v[4:5], off offset:3072
	s_movk_i32 s4, 0x1000
	v_add_co_u32_e32 v2, vcc, s4, v2
	s_mov_b32 s8, 0xf800000
	s_nop 0
	v_addc_co_u32_e32 v3, vcc, 0, v3, vcc
	global_load_dwordx4 v[34:37], v[2:3], off
	v_add_co_u32_e32 v4, vcc, s4, v4
	s_movk_i32 s2, 0x1000
	s_nop 0
	v_addc_co_u32_e32 v5, vcc, 0, v5, vcc
	global_load_dwordx4 v[18:21], v[4:5], off
	global_load_dwordx4 v[14:17], v[2:3], off offset:1024
	global_load_dwordx4 v[22:25], v[4:5], off offset:1024
	global_load_dwordx4 v[26:29], v[2:3], off offset:2048
	global_load_dwordx4 v[6:9], v[4:5], off offset:2048
	global_load_dwordx4 v[10:13], v[2:3], off offset:3072
	s_nop 0
	global_load_dwordx4 v[2:5], v[4:5], off offset:3072
	s_waitcnt vmcnt(15)
	v_mul_f32_e32 v84, v63, v63
	v_fmac_f32_e32 v84, v62, v62
	s_waitcnt vmcnt(13)
	v_mul_f32_e32 v86, v55, v55
	v_fmac_f32_e32 v86, v54, v54
	v_fmac_f32_e32 v84, v64, v64
	v_fmac_f32_e32 v86, v56, v56
	v_fmac_f32_e32 v84, v65, v65
	v_fmac_f32_e32 v86, v57, v57
	v_mul_f32_e32 v85, v59, v59
	v_add_f32_e32 v84, v84, v86
	s_waitcnt vmcnt(12)
	v_mul_f32_e32 v86, v51, v51
	v_fmac_f32_e32 v85, v58, v58
	v_fmac_f32_e32 v86, v50, v50
	v_fmac_f32_e32 v85, v60, v60
	v_fmac_f32_e32 v86, v52, v52
	v_fmac_f32_e32 v85, v61, v61
	v_fmac_f32_e32 v86, v53, v53
	v_add_f32_e32 v85, v85, v86
	s_waitcnt vmcnt(11)
	v_mul_f32_e32 v86, v47, v47
	v_fmac_f32_e32 v86, v46, v46
	v_fmac_f32_e32 v86, v48, v48
	v_fmac_f32_e32 v86, v49, v49
	v_add_f32_e32 v84, v84, v86
	s_waitcnt vmcnt(10)
	v_mul_f32_e32 v86, v43, v43
	v_fmac_f32_e32 v86, v42, v42
	v_fmac_f32_e32 v86, v44, v44
	v_fmac_f32_e32 v86, v45, v45
	v_add_f32_e32 v85, v85, v86
	s_waitcnt vmcnt(9)
	v_mul_f32_e32 v86, v39, v39
	v_fmac_f32_e32 v86, v38, v38
	v_fmac_f32_e32 v86, v40, v40
	v_fmac_f32_e32 v86, v41, v41
	v_add_f32_e32 v84, v84, v86
	s_waitcnt vmcnt(8)
	v_mul_f32_e32 v86, v31, v31
	v_fmac_f32_e32 v86, v30, v30
	v_fmac_f32_e32 v86, v32, v32
	v_fmac_f32_e32 v86, v33, v33
	v_add_f32_e32 v85, v85, v86
	s_waitcnt vmcnt(7)
	v_mul_f32_e32 v86, v35, v35
	v_fmac_f32_e32 v86, v34, v34
	v_fmac_f32_e32 v86, v36, v36
	v_fmac_f32_e32 v86, v37, v37
	v_add_f32_e32 v84, v84, v86
	s_waitcnt vmcnt(6)
	v_mul_f32_e32 v86, v19, v19
	v_fmac_f32_e32 v86, v18, v18
	v_fmac_f32_e32 v86, v20, v20
	v_fmac_f32_e32 v86, v21, v21
	v_add_f32_e32 v85, v85, v86
	s_waitcnt vmcnt(5)
	v_mul_f32_e32 v86, v15, v15
	v_fmac_f32_e32 v86, v14, v14
	v_fmac_f32_e32 v86, v16, v16
	v_fmac_f32_e32 v86, v17, v17
	v_add_f32_e32 v88, v84, v86
	s_waitcnt vmcnt(4)
	v_mul_f32_e32 v84, v23, v23
	v_fmac_f32_e32 v84, v22, v22
	v_fmac_f32_e32 v84, v24, v24
	v_fmac_f32_e32 v84, v25, v25
	s_waitcnt vmcnt(3)
	v_mov_b32_e32 v86, v27
	s_waitcnt vmcnt(1)
	v_mov_b32_e32 v87, v11
	v_add_f32_e32 v89, v85, v84
	v_mov_b32_e32 v84, v26
	v_mov_b32_e32 v85, v10
	v_pk_mul_f32 v[86:87], v[86:87], v[86:87]
	s_nop 0
	v_pk_fma_f32 v[84:85], v[84:85], v[84:85], v[86:87]
	v_mov_b32_e32 v86, v28
	v_mov_b32_e32 v87, v12
	v_pk_fma_f32 v[84:85], v[86:87], v[86:87], v[84:85]
	v_mov_b32_e32 v86, v29
	v_mov_b32_e32 v87, v13
	v_pk_fma_f32 v[84:85], v[86:87], v[86:87], v[84:85]
	v_mov_b32_e32 v86, v7
	v_add_f32_e32 v84, v88, v84
	s_waitcnt vmcnt(0)
	v_mov_b32_e32 v87, v3
	v_add_f32_e32 v88, v84, v85
	v_mov_b32_e32 v84, v6
	v_mov_b32_e32 v85, v2
	v_pk_mul_f32 v[86:87], v[86:87], v[86:87]
	s_nop 0
	v_pk_fma_f32 v[84:85], v[84:85], v[84:85], v[86:87]
	v_mov_b32_e32 v86, v8
	v_mov_b32_e32 v87, v4
	v_pk_fma_f32 v[84:85], v[86:87], v[86:87], v[84:85]
	v_mov_b32_e32 v86, v9
	v_mov_b32_e32 v87, v5
	v_pk_fma_f32 v[84:85], v[86:87], v[86:87], v[84:85]
	s_nop 0
	v_add_f32_e32 v84, v89, v84
	v_add_f32_e32 v84, v84, v85
	ds_bpermute_b32 v85, v92, v88
	ds_bpermute_b32 v86, v92, v84
	s_waitcnt lgkmcnt(1)
	v_add_f32_e32 v85, v88, v85
	s_waitcnt lgkmcnt(0)
	v_add_f32_e32 v84, v84, v86
	ds_bpermute_b32 v86, v93, v85
	s_waitcnt lgkmcnt(0)
	v_add_f32_e32 v85, v85, v86
	ds_bpermute_b32 v86, v93, v84
	s_waitcnt lgkmcnt(0)
	v_add_f32_e32 v84, v84, v86
	ds_bpermute_b32 v86, v94, v85
	s_waitcnt lgkmcnt(0)
	v_add_f32_e32 v85, v85, v86
	ds_bpermute_b32 v86, v94, v84
	s_waitcnt lgkmcnt(0)
	v_add_f32_e32 v84, v84, v86
	ds_bpermute_b32 v86, v95, v85
	s_waitcnt lgkmcnt(0)
	v_add_f32_e32 v85, v85, v86
	ds_bpermute_b32 v86, v95, v84
	s_waitcnt lgkmcnt(0)
	v_add_f32_e32 v84, v84, v86
	ds_bpermute_b32 v86, v96, v85
	s_waitcnt lgkmcnt(0)
	v_add_f32_e32 v85, v85, v86
	ds_bpermute_b32 v86, v96, v84
	s_waitcnt lgkmcnt(0)
	v_add_f32_e32 v84, v84, v86
	ds_bpermute_b32 v86, v97, v85
	s_waitcnt lgkmcnt(0)
	v_add_f32_e32 v85, v85, v86
	ds_bpermute_b32 v86, v97, v84
	s_waitcnt lgkmcnt(0)
; __device__ __forceinline__ unsigned cvt_pk_bf16(float lo, float hi) { const f32x2 v = {lo, hi}; const bf16x2_t b = __builtin_convertvector(v, bf16x2_t); return __builtin_bit_cast(unsigned, b); }
; __device__ __forceinline__ void norm_rows(const XSrc src, const float* gain, bf16_t* dbf, float* df32) {
;     ...
;         const float rs = 1.0f / sqrtf(ss * (1.0f / DM) + 1e-6f), rt = 1.0f / sqrtf(st * (1.0f / DM) + 1e-6f);
; #pragma unroll
;         for (int i = 0; i < 8; ++i) {
;             const f32x4 gn = *(const f32x4*)(gain + i * 256 + lane * 4);
;             const f32x4 y = v[i] * rs * gn, y2 = u[i] * rt * gn;
;             if (dbf) { u32x2 w; w.x = cvt_pk_bf16(y[0], y[1]); w.y = cvt_pk_bf16(y[2], y[3]); *(u32x2*)(dbf + (size_t)row * DM + i * 256 + lane * 4) = w;
;                        if (row2 != row) { w.x = cvt_pk_bf16(y2[0], y2[1]); w.y = cvt_pk_bf16(y2[2], y2[3]); *(u32x2*)(dbf + (size_t)row2 * DM + i * 256 + lane * 4) = w; } }
;             if (df32) { *(f32x4*)(df32 + (size_t)row * DM + i * 256 + lane * 4) = y; if (row2 != row) *(f32x4*)(df32 + (size_t)row2 * DM + i * 256 + lane * 4) = y2; }
	v_add_f32_e32 v86, v84, v86
	v_fmamk_f32 v84, v85, 0x3a000000, v183
	v_cmp_gt_f32_e32 vcc, s8, v84
	v_mul_f32_e32 v85, 0x4f800000, v84
	s_nop 0
	v_cndmask_b32_e32 v84, v84, v85, vcc
	v_sqrt_f32_e32 v85, v84
	s_nop 0
	v_add_u32_e32 v87, -1, v85
	v_fma_f32 v88, -v87, v85, v84
	v_cmp_ge_f32_e64 s[4:5], 0, v88
	v_add_u32_e32 v88, 1, v85
	s_nop 0
	v_cndmask_b32_e64 v87, v85, v87, s[4:5]
	v_fma_f32 v85, -v88, v85, v84
	v_cmp_lt_f32_e64 s[4:5], 0, v85
	s_nop 1
	v_cndmask_b32_e64 v85, v87, v88, s[4:5]
	v_mul_f32_e32 v87, 0x37800000, v85
	v_cndmask_b32_e32 v85, v85, v87, vcc
	v_cmp_class_f32_e32 vcc, v84, v184
	s_nop 1
	v_cndmask_b32_e32 v84, v85, v84, vcc
	v_div_scale_f32 v85, s[4:5], v84, v84, 1.0
	v_rcp_f32_e32 v87, v85
	s_nop 0
	v_fma_f32 v88, -v85, v87, 1.0
	v_fmac_f32_e32 v87, v88, v87
	v_div_scale_f32 v88, vcc, 1.0, v84, 1.0
	v_mul_f32_e32 v89, v88, v87
	v_fma_f32 v90, -v85, v89, v88
	v_fmac_f32_e32 v89, v90, v87
	v_fma_f32 v85, -v85, v89, v88
	v_div_fmas_f32 v85, v85, v87, v89
	v_div_fixup_f32 v84, v85, v84, 1.0
	v_fmamk_f32 v85, v86, 0x3a000000, v183
	v_cmp_gt_f32_e32 vcc, s8, v85
	v_mul_f32_e32 v86, 0x4f800000, v85
	s_nop 0
	v_cndmask_b32_e32 v85, v85, v86, vcc
	v_sqrt_f32_e32 v86, v85
	s_nop 0
	v_add_u32_e32 v87, -1, v86
	v_fma_f32 v88, -v87, v86, v85
	v_cmp_ge_f32_e64 s[4:5], 0, v88
	v_add_u32_e32 v88, 1, v86
	s_nop 0
	v_cndmask_b32_e64 v87, v86, v87, s[4:5]
	v_fma_f32 v86, -v88, v86, v85
	v_cmp_lt_f32_e64 s[4:5], 0, v86
	s_nop 1
	v_cndmask_b32_e64 v86, v87, v88, s[4:5]
	v_mul_f32_e32 v87, 0x37800000, v86
	v_cndmask_b32_e32 v86, v86, v87, vcc
	v_cmp_class_f32_e32 vcc, v85, v184
	s_nop 1
	v_cndmask_b32_e32 v85, v86, v85, vcc
	v_div_scale_f32 v86, s[4:5], v85, v85, 1.0
	v_rcp_f32_e32 v87, v86
	v_pk_mul_f32 v[62:63], v[62:63], v[84:85] op_sel_hi:[1,0]
	v_pk_mul_f32 v[64:65], v[64:65], v[84:85] op_sel_hi:[1,0]
	v_fma_f32 v88, -v86, v87, 1.0
	v_fmac_f32_e32 v87, v88, v87
	v_div_scale_f32 v88, vcc, 1.0, v85, 1.0
	v_mul_f32_e32 v89, v88, v87
	v_fma_f32 v90, -v86, v89, v88
	v_fmac_f32_e32 v89, v90, v87
	v_fma_f32 v86, -v86, v89, v88
	v_div_fmas_f32 v86, v86, v87, v89
	v_div_fixup_f32 v88, v86, v85, 1.0
	v_lshlrev_b64 v[86:87], 12, v[66:67]
	v_cmp_ne_u32_e32 vcc, v66, v68
	v_lshlrev_b64 v[66:67], 12, v[68:69]
	v_lshl_add_u64 v[90:91], v[72:73], 0, v[86:87]
	v_lshl_add_u64 v[86:87], v[72:73], 0, v[66:67]
	v_mov_b32_e32 v89, v88
	v_pk_mul_f32 v[64:65], v[198:199], v[64:65]
	v_pk_mul_f32 v[62:63], v[196:197], v[62:63]
	s_nop 0
	v_cvt_pk_bf16_f32 v62, v62, v63
	v_cvt_pk_bf16_f32 v63, v64, v65
	global_store_dwordx2 v[90:91], v[62:63], off
	s_and_saveexec_b64 s[4:5], vcc
	s_cbranch_execz .LBB0_1474
	v_mov_b32_e32 v62, v88
	v_mov_b32_e32 v63, v88
	v_pk_mul_f32 v[60:61], v[60:61], v[62:63]
	v_pk_mul_f32 v[58:59], v[58:59], v[88:89]
	v_pk_mul_f32 v[60:61], v[198:199], v[60:61]
	v_pk_mul_f32 v[58:59], v[196:197], v[58:59]
	s_nop 0
	v_cvt_pk_bf16_f32 v58, v58, v59
	v_cvt_pk_bf16_f32 v59, v60, v61
	global_store_dwordx2 v[86:87], v[58:59], off
.LBB0_1474:
	s_or_b64 exec, exec, s[4:5]
	v_mov_b32_e32 v85, v84
	v_mov_b32_e32 v62, v84
	v_mov_b32_e32 v63, v84
	v_pk_mul_f32 v[56:57], v[56:57], v[62:63]
	v_pk_mul_f32 v[54:55], v[54:55], v[84:85]
	v_pk_mul_f32 v[56:57], v[56:57], v[202:203]
	v_pk_mul_f32 v[54:55], v[54:55], v[200:201]
	s_nop 0
	v_cvt_pk_bf16_f32 v54, v54, v55
	v_cvt_pk_bf16_f32 v55, v56, v57
	global_store_dwordx2 v[90:91], v[54:55], off offset:512
	s_and_saveexec_b64 s[4:5], vcc
	s_cbranch_execz .LBB0_1476
	v_mov_b32_e32 v54, v88
	v_mov_b32_e32 v55, v88
	v_pk_mul_f32 v[52:53], v[52:53], v[54:55]
	v_pk_mul_f32 v[50:51], v[50:51], v[88:89]
	v_pk_mul_f32 v[52:53], v[52:53], v[202:203]
	v_pk_mul_f32 v[50:51], v[50:51], v[200:201]
	s_nop 0
	v_cvt_pk_bf16_f32 v50, v50, v51
	v_cvt_pk_bf16_f32 v51, v52, v53
	global_store_dwordx2 v[86:87], v[50:51], off offset:512
.LBB0_1476:
	s_or_b64 exec, exec, s[4:5]
	v_pk_mul_f32 v[48:49], v[48:49], v[62:63]
	v_pk_mul_f32 v[46:47], v[46:47], v[84:85]
	v_pk_mul_f32 v[48:49], v[48:49], v[206:207]
	v_pk_mul_f32 v[46:47], v[46:47], v[204:205]
	s_nop 0
	v_cvt_pk_bf16_f32 v46, v46, v47
	v_cvt_pk_bf16_f32 v47, v48, v49
	global_store_dwordx2 v[90:91], v[46:47], off offset:1024
	s_and_saveexec_b64 s[4:5], vcc
	s_cbranch_execz .LBB0_1478
	v_mov_b32_e32 v46, v88
	v_mov_b32_e32 v47, v88
	v_pk_mul_f32 v[44:45], v[44:45], v[46:47]
	v_pk_mul_f32 v[42:43], v[42:43], v[88:89]
	v_pk_mul_f32 v[44:45], v[44:45], v[206:207]
	v_pk_mul_f32 v[42:43], v[42:43], v[204:205]
	s_nop 0
	v_cvt_pk_bf16_f32 v42, v42, v43
	v_cvt_pk_bf16_f32 v43, v44, v45
	global_store_dwordx2 v[86:87], v[42:43], off offset:1024
; __device__ __forceinline__ unsigned cvt_pk_bf16(float lo, float hi) { const f32x2 v = {lo, hi}; const bf16x2_t b = __builtin_convertvector(v, bf16x2_t); return __builtin_bit_cast(unsigned, b); }
; __device__ __forceinline__ void norm_rows(const XSrc src, const float* gain, bf16_t* dbf, float* df32) {
;     ...
;         for (int i = 0; i < 8; ++i) {
;             const f32x4 gn = *(const f32x4*)(gain + i * 256 + lane * 4);
;             const f32x4 y = v[i] * rs * gn, y2 = u[i] * rt * gn;
;             if (dbf) { u32x2 w; w.x = cvt_pk_bf16(y[0], y[1]); w.y = cvt_pk_bf16(y[2], y[3]); *(u32x2*)(dbf + (size_t)row * DM + i * 256 + lane * 4) = w;
;                        if (row2 != row) { w.x = cvt_pk_bf16(y2[0], y2[1]); w.y = cvt_pk_bf16(y2[2], y2[3]); *(u32x2*)(dbf + (size_t)row2 * DM + i * 256 + lane * 4) = w; } }
;             if (df32) { *(f32x4*)(df32 + (size_t)row * DM + i * 256 + lane * 4) = y; if (row2 != row) *(f32x4*)(df32 + (size_t)row2 * DM + i * 256 + lane * 4) = y2; }
.LBB0_1478:
	s_or_b64 exec, exec, s[4:5]
	v_mov_b32_e32 v46, v84
	v_mov_b32_e32 v47, v84
	v_pk_mul_f32 v[38:39], v[38:39], v[84:85]
	v_pk_mul_f32 v[40:41], v[40:41], v[46:47]
	v_pk_mul_f32 v[38:39], v[38:39], v[208:209]
	v_pk_mul_f32 v[40:41], v[40:41], v[210:211]
	v_cvt_pk_bf16_f32 v38, v38, v39
	v_cvt_pk_bf16_f32 v39, v40, v41
	global_store_dwordx2 v[90:91], v[38:39], off offset:1536
	s_and_saveexec_b64 s[4:5], vcc
	s_cbranch_execz .LBB0_1480
	v_mov_b32_e32 v38, v88
	v_mov_b32_e32 v39, v88
	v_pk_mul_f32 v[32:33], v[32:33], v[38:39]
	v_pk_mul_f32 v[30:31], v[30:31], v[88:89]
	v_pk_mul_f32 v[32:33], v[32:33], v[210:211]
	v_pk_mul_f32 v[30:31], v[30:31], v[208:209]
	s_nop 0
	v_cvt_pk_bf16_f32 v30, v30, v31
	v_cvt_pk_bf16_f32 v31, v32, v33
	global_store_dwordx2 v[86:87], v[30:31], off offset:1536
.LBB0_1480:
	s_or_b64 exec, exec, s[4:5]
	v_pk_mul_f32 v[36:37], v[36:37], v[46:47]
	v_pk_mul_f32 v[34:35], v[34:35], v[84:85]
	v_pk_mul_f32 v[36:37], v[36:37], v[214:215]
	v_pk_mul_f32 v[34:35], v[34:35], v[212:213]
	s_nop 0
	v_cvt_pk_bf16_f32 v34, v34, v35
	v_cvt_pk_bf16_f32 v35, v36, v37
	global_store_dwordx2 v[90:91], v[34:35], off offset:2048
	s_and_saveexec_b64 s[4:5], vcc
	s_cbranch_execz .LBB0_1482
	v_mov_b32_e32 v34, v88
	v_mov_b32_e32 v35, v88
	v_pk_mul_f32 v[20:21], v[20:21], v[34:35]
	v_pk_mul_f32 v[18:19], v[18:19], v[88:89]
	v_pk_mul_f32 v[20:21], v[20:21], v[214:215]
	v_pk_mul_f32 v[18:19], v[18:19], v[212:213]
	s_nop 0
	v_cvt_pk_bf16_f32 v18, v18, v19
	v_cvt_pk_bf16_f32 v19, v20, v21
	global_store_dwordx2 v[86:87], v[18:19], off offset:2048
.LBB0_1482:
	s_or_b64 exec, exec, s[4:5]
	v_mov_b32_e32 v30, v84
	v_mov_b32_e32 v31, v84
	v_pk_mul_f32 v[14:15], v[14:15], v[84:85]
	v_pk_mul_f32 v[16:17], v[16:17], v[30:31]
	v_pk_mul_f32 v[14:15], v[14:15], v[216:217]
	v_pk_mul_f32 v[16:17], v[16:17], v[218:219]
	v_cvt_pk_bf16_f32 v14, v14, v15
	v_cvt_pk_bf16_f32 v15, v16, v17
	global_store_dwordx2 v[90:91], v[14:15], off offset:2560
	s_and_saveexec_b64 s[4:5], vcc
	s_cbranch_execz .LBB0_1484
	v_mov_b32_e32 v14, v88
	v_mov_b32_e32 v15, v88
	v_pk_mul_f32 v[14:15], v[24:25], v[14:15]
	v_pk_mul_f32 v[16:17], v[22:23], v[88:89]
	v_pk_mul_f32 v[14:15], v[14:15], v[218:219]
	v_pk_mul_f32 v[16:17], v[16:17], v[216:217]
	s_nop 0
	v_cvt_pk_bf16_f32 v16, v16, v17
	v_cvt_pk_bf16_f32 v17, v14, v15
	global_store_dwordx2 v[86:87], v[16:17], off offset:2560
.LBB0_1484:
	s_or_b64 exec, exec, s[4:5]
	v_pk_mul_f32 v[18:19], v[28:29], v[30:31]
	v_pk_mul_f32 v[20:21], v[26:27], v[84:85]
	v_pk_mul_f32 v[18:19], v[18:19], v[222:223]
	v_pk_mul_f32 v[20:21], v[20:21], v[220:221]
	s_nop 0
	v_cvt_pk_bf16_f32 v20, v20, v21
	v_cvt_pk_bf16_f32 v21, v18, v19
	global_store_dwordx2 v[90:91], v[20:21], off offset:3072
	s_and_saveexec_b64 s[4:5], vcc
	s_cbranch_execz .LBB0_1486
	v_mov_b32_e32 v18, v88
	v_mov_b32_e32 v19, v88
	v_pk_mul_f32 v[8:9], v[8:9], v[18:19]
	v_pk_mul_f32 v[6:7], v[6:7], v[88:89]
	v_pk_mul_f32 v[8:9], v[8:9], v[222:223]
	v_pk_mul_f32 v[6:7], v[6:7], v[220:221]
	s_nop 0
	v_cvt_pk_bf16_f32 v6, v6, v7
	v_cvt_pk_bf16_f32 v7, v8, v9
	global_store_dwordx2 v[86:87], v[6:7], off offset:3072
.LBB0_1486:
	s_or_b64 exec, exec, s[4:5]
	v_mov_b32_e32 v14, v84
	v_mov_b32_e32 v15, v84
	v_pk_mul_f32 v[10:11], v[10:11], v[84:85]
	v_pk_mul_f32 v[12:13], v[12:13], v[14:15]
	v_pk_mul_f32 v[10:11], v[10:11], v[224:225]
	v_pk_mul_f32 v[12:13], v[12:13], v[226:227]
	v_cvt_pk_bf16_f32 v10, v10, v11
	v_cvt_pk_bf16_f32 v11, v12, v13
	global_store_dwordx2 v[90:91], v[10:11], off offset:3584
	s_and_saveexec_b64 s[4:5], vcc
	s_cbranch_execz .LBB0_1471
	v_mov_b32_e32 v10, v88
	v_mov_b32_e32 v11, v88
	v_pk_mul_f32 v[4:5], v[4:5], v[10:11]
	v_pk_mul_f32 v[2:3], v[2:3], v[88:89]
	v_pk_mul_f32 v[4:5], v[4:5], v[226:227]
	v_pk_mul_f32 v[2:3], v[2:3], v[224:225]
	s_nop 0
	v_cvt_pk_bf16_f32 v2, v2, v3
	v_cvt_pk_bf16_f32 v3, v4, v5
	global_store_dwordx2 v[86:87], v[2:3], off offset:3584
	s_branch .LBB0_1471

; __device__ __forceinline__ int fresh_tid() { int t = threadIdx.x; asm volatile("" : "+v"(t)); return t; }
; __device__ __forceinline__ int fresh_bid() { int t = blockIdx.x; asm volatile("" : "+s"(t)); return t; }
; __device__ __forceinline__ void norm_rows(const XSrc src, const float* gain, bf16_t* dbf, float* df32) {
;     const int lane = fresh_tid() & 63, gw = fresh_bid() * 8 + (fresh_tid() >> 6), nw = gridDim.x * 8;
;     for (int row = gw; row < MROWS; row += 2 * nw) {
;         const int row2 = row + nw < MROWS ? row + nw : row;
;         const float* xp = src.row(row); const float* xq = src.row(row2);
;         f32x4 v[8], u[8]; float ss = 0.f, st = 0.f;
; #pragma unroll
;         for (int i = 0; i < 8; ++i) { v[i] = *(const f32x4*)(xp + i * 256 + lane * 4); u[i] = *(const f32x4*)(xq + i * 256 + lane * 4); }
; #pragma unroll
;         for (int i = 0; i < 8; ++i) { ss += v[i][0] * v[i][0] + v[i][1] * v[i][1] + v[i][2] * v[i][2] + v[i][3] * v[i][3]; st += u[i][0] * u[i][0] + u[i][1] * u[i][1] + u[i][2] * u[i][2] + u[i][3] * u[i][3]; }
; #pragma unroll
;         for (int o = 32; o > 0; o >>= 1) { ss += __shfl_xor(ss, o); st += __shfl_xor(st, o); }
;         const float rs = 1.0f / sqrtf(ss * (1.0f / DM) + 1e-6f), rt = 1.0f / sqrtf(st * (1.0f / DM) + 1e-6f);
; #pragma unroll
;         for (int i = 0; i < 8; ++i) {
;             const f32x4 gn = *(const f32x4*)(gain + i * 256 + lane * 4);
; __global__ void __launch_bounds__(512) hybrid_fwd(Params p_unused) {
;     ...
;           if (l == 0) norm_rows(s, p->in[6] + DM, (bf16_t*)(p->ws + WS_XN), nullptr); else norm_rows(s, p->in[29], nullptr, p->out + O_Y); }
.LBB0_1761:
	s_andn2_b64 vcc, exec, s[4:5]
	s_cbranch_vccnz .LBB0_1782
	v_mov_b32_e32 v0, v176
	s_mov_b32 s4, s94
	v_mov_b32_e32 v2, v176
	s_nop 0
	v_ashrrev_i32_e32 v2, 6, v2
	v_lshl_add_u32 v66, s4, 3, v2
	s_movk_i32 s4, 0x2080
	v_cmp_gt_i32_e32 vcc, s4, v66
	s_and_saveexec_b64 s[10:11], vcc
	s_cbranch_execz .LBB0_1781
	s_load_dwordx2 s[4:5], s[8:9], 0x30
	v_lshlrev_b32_e32 v0, 2, v0
	v_and_b32_e32 v4, 0xfc, v0
	v_and_b32_e32 v0, 64, v181
	v_add_u32_e32 v6, 64, v0
	v_lshlrev_b32_e32 v0, 2, v4
	v_lshlrev_b32_e32 v4, 1, v4
	v_mov_b32_e32 v5, v1
	s_waitcnt lgkmcnt(0)
	v_lshl_add_u64 v[2:3], s[4:5], 0, v[0:1]
	v_lshl_add_u64 v[4:5], s[6:7], 0, v[4:5]
	s_mov_b64 s[4:5], 0x12200000
	v_lshl_add_u64 v[72:73], v[4:5], 0, s[4:5]
	v_xor_b32_e32 v4, 32, v181
	v_cmp_lt_i32_e32 vcc, v4, v6
	s_mov_b64 s[4:5], 0x3000
	v_lshl_add_u64 v[74:75], v[2:3], 0, s[4:5]
	v_cndmask_b32_e32 v4, v181, v4, vcc
	v_lshlrev_b32_e32 v92, 2, v4
	v_xor_b32_e32 v4, 16, v181
	v_cmp_lt_i32_e32 vcc, v4, v6
	s_mov_b64 s[4:5], 0x3400
	v_lshl_add_u64 v[76:77], v[2:3], 0, s[4:5]
	v_cndmask_b32_e32 v4, v181, v4, vcc
	v_lshlrev_b32_e32 v93, 2, v4
	v_xor_b32_e32 v4, 8, v181
	v_cmp_lt_i32_e32 vcc, v4, v6
	s_mov_b64 s[4:5], 0x3800
	v_lshl_add_u64 v[78:79], v[2:3], 0, s[4:5]
	v_cndmask_b32_e32 v4, v181, v4, vcc
	v_lshlrev_b32_e32 v94, 2, v4
	v_xor_b32_e32 v4, 4, v181
	v_cmp_lt_i32_e32 vcc, v4, v6
	s_mov_b64 s[4:5], 0x3c00
	v_lshl_add_u64 v[70:71], v[2:3], 0, s[68:69]
	v_cndmask_b32_e32 v4, v181, v4, vcc
	v_lshlrev_b32_e32 v95, 2, v4
	v_xor_b32_e32 v4, 2, v181
	v_cmp_lt_i32_e32 vcc, v4, v6
	v_lshl_add_u64 v[80:81], v[2:3], 0, s[4:5]
	v_lshl_add_u64 v[82:83], s[0:1], 0, v[0:1]
	v_cndmask_b32_e32 v4, v181, v4, vcc
	v_lshlrev_b32_e32 v96, 2, v4
	v_xor_b32_e32 v4, 1, v181
	v_cmp_lt_i32_e32 vcc, v4, v6
	s_mov_b64 s[0:1], 0
	s_nop 0
	v_cndmask_b32_e32 v4, v181, v4, vcc
	v_lshlrev_b32_e32 v97, 2, v4
	global_load_dwordx4 v[196:199], v[70:71], off
	global_load_dwordx4 v[200:203], v[70:71], off offset:1024
	global_load_dwordx4 v[204:207], v[70:71], off offset:2048
	global_load_dwordx4 v[208:211], v[70:71], off offset:3072
	global_load_dwordx4 v[212:215], v[74:75], off
	global_load_dwordx4 v[216:219], v[76:77], off
	global_load_dwordx4 v[220:223], v[78:79], off
	global_load_dwordx4 v[224:227], v[80:81], off
	s_branch .LBB0_1765

; __device__ __forceinline__ void norm_rows(const XSrc src, const float* gain, bf16_t* dbf, float* df32) {
;     ...
;     for (int row = gw; row < MROWS; row += 2 * nw) {
;         const int row2 = row + nw < MROWS ? row + nw : row;
;         const float* xp = src.row(row); const float* xq = src.row(row2);
;         f32x4 v[8], u[8]; float ss = 0.f, st = 0.f;
; #pragma unroll
;         for (int i = 0; i < 8; ++i) { v[i] = *(const f32x4*)(xp + i * 256 + lane * 4); u[i] = *(const f32x4*)(xq + i * 256 + lane * 4); }
; #pragma unroll
;         for (int i = 0; i < 8; ++i) { ss += v[i][0] * v[i][0] + v[i][1] * v[i][1] + v[i][2] * v[i][2] + v[i][3] * v[i][3]; st += u[i][0] * u[i][0] + u[i][1] * u[i][1] + u[i][2] * u[i][2] + u[i][3] * u[i][3]; }
; #pragma unroll
;         for (int o = 32; o > 0; o >>= 1) { ss += __shfl_xor(ss, o); st += __shfl_xor(st, o); }
.LBB0_1765:
	v_add_u32_e32 v0, s97, v66
	s_movk_i32 s2, 0x2080
	v_cmp_gt_i32_e32 vcc, s2, v0
	v_ashrrev_i32_e32 v67, 31, v66
	v_lshlrev_b64 v[2:3], 13, v[66:67]
	v_cndmask_b32_e32 v68, v66, v0, vcc
	v_cmp_gt_i32_e32 vcc, s38, v68
	v_add_u32_e32 v4, 0xffffdf00, v68
	v_ashrrev_i32_e32 v69, 31, v68
	v_cndmask_b32_e32 v5, 0, v69, vcc
	v_cndmask_b32_e32 v4, v4, v68, vcc
	v_lshlrev_b64 v[4:5], 13, v[4:5]
	v_lshl_add_u64 v[2:3], v[82:83], 0, v[2:3]
	v_lshl_add_u64 v[4:5], v[82:83], 0, v[4:5]
	global_load_dwordx4 v[62:65], v[2:3], off
	global_load_dwordx4 v[58:61], v[4:5], off
	global_load_dwordx4 v[54:57], v[2:3], off offset:1024
	global_load_dwordx4 v[50:53], v[4:5], off offset:1024
	global_load_dwordx4 v[46:49], v[2:3], off offset:2048
	global_load_dwordx4 v[42:45], v[4:5], off offset:2048
	global_load_dwordx4 v[38:41], v[2:3], off offset:3072
	global_load_dwordx4 v[30:33], v[4:5], off offset:3072
	s_movk_i32 s4, 0x1000
	v_add_co_u32_e32 v2, vcc, s4, v2
	s_mov_b32 s6, 0xf800000
	s_nop 0
	v_addc_co_u32_e32 v3, vcc, 0, v3, vcc
	global_load_dwordx4 v[34:37], v[2:3], off
	v_add_co_u32_e32 v4, vcc, s4, v4
	s_movk_i32 s2, 0x1000
	s_nop 0
	v_addc_co_u32_e32 v5, vcc, 0, v5, vcc
	global_load_dwordx4 v[18:21], v[4:5], off
	global_load_dwordx4 v[14:17], v[2:3], off offset:1024
	global_load_dwordx4 v[22:25], v[4:5], off offset:1024
	global_load_dwordx4 v[26:29], v[2:3], off offset:2048
	global_load_dwordx4 v[6:9], v[4:5], off offset:2048
	global_load_dwordx4 v[10:13], v[2:3], off offset:3072
	s_nop 0
	global_load_dwordx4 v[2:5], v[4:5], off offset:3072
	s_waitcnt vmcnt(15)
	v_mul_f32_e32 v84, v63, v63
	v_fmac_f32_e32 v84, v62, v62
	s_waitcnt vmcnt(13)
	v_mul_f32_e32 v86, v55, v55
	v_fmac_f32_e32 v86, v54, v54
	v_fmac_f32_e32 v84, v64, v64
	v_fmac_f32_e32 v86, v56, v56
	v_fmac_f32_e32 v84, v65, v65
	v_fmac_f32_e32 v86, v57, v57
	v_mul_f32_e32 v85, v59, v59
	v_add_f32_e32 v84, v84, v86
	s_waitcnt vmcnt(12)
	v_mul_f32_e32 v86, v51, v51
	v_fmac_f32_e32 v85, v58, v58
	v_fmac_f32_e32 v86, v50, v50
	v_fmac_f32_e32 v85, v60, v60
	v_fmac_f32_e32 v86, v52, v52
	v_fmac_f32_e32 v85, v61, v61
	v_fmac_f32_e32 v86, v53, v53
	v_add_f32_e32 v85, v85, v86
	s_waitcnt vmcnt(11)
	v_mul_f32_e32 v86, v47, v47
	v_fmac_f32_e32 v86, v46, v46
	v_fmac_f32_e32 v86, v48, v48
	v_fmac_f32_e32 v86, v49, v49
	v_add_f32_e32 v84, v84, v86
	s_waitcnt vmcnt(10)
	v_mul_f32_e32 v86, v43, v43
	v_fmac_f32_e32 v86, v42, v42
	v_fmac_f32_e32 v86, v44, v44
	v_fmac_f32_e32 v86, v45, v45
	v_add_f32_e32 v85, v85, v86
	s_waitcnt vmcnt(9)
	v_mul_f32_e32 v86, v39, v39
	v_fmac_f32_e32 v86, v38, v38
	v_fmac_f32_e32 v86, v40, v40
	v_fmac_f32_e32 v86, v41, v41
	v_add_f32_e32 v84, v84, v86
	s_waitcnt vmcnt(8)
	v_mul_f32_e32 v86, v31, v31
	v_fmac_f32_e32 v86, v30, v30
	v_fmac_f32_e32 v86, v32, v32
	v_fmac_f32_e32 v86, v33, v33
	v_add_f32_e32 v85, v85, v86
	s_waitcnt vmcnt(7)
	v_mul_f32_e32 v86, v35, v35
	v_fmac_f32_e32 v86, v34, v34
	v_fmac_f32_e32 v86, v36, v36
	v_fmac_f32_e32 v86, v37, v37
	v_add_f32_e32 v84, v84, v86
	s_waitcnt vmcnt(6)
	v_mul_f32_e32 v86, v19, v19
	v_fmac_f32_e32 v86, v18, v18
	v_fmac_f32_e32 v86, v20, v20
	v_fmac_f32_e32 v86, v21, v21
	v_add_f32_e32 v85, v85, v86
	s_waitcnt vmcnt(5)
	v_mul_f32_e32 v86, v15, v15
	v_fmac_f32_e32 v86, v14, v14
	v_fmac_f32_e32 v86, v16, v16
	v_fmac_f32_e32 v86, v17, v17
	v_add_f32_e32 v88, v84, v86
	s_waitcnt vmcnt(4)
	v_mul_f32_e32 v84, v23, v23
	v_fmac_f32_e32 v84, v22, v22
	v_fmac_f32_e32 v84, v24, v24
	v_fmac_f32_e32 v84, v25, v25
	s_waitcnt vmcnt(3)
	v_mov_b32_e32 v86, v27
	s_waitcnt vmcnt(1)
	v_mov_b32_e32 v87, v11
	v_add_f32_e32 v89, v85, v84
	v_mov_b32_e32 v84, v26
	v_mov_b32_e32 v85, v10
	v_pk_mul_f32 v[86:87], v[86:87], v[86:87]
	s_nop 0
	v_pk_fma_f32 v[84:85], v[84:85], v[84:85], v[86:87]
	v_mov_b32_e32 v86, v28
	v_mov_b32_e32 v87, v12
	v_pk_fma_f32 v[84:85], v[86:87], v[86:87], v[84:85]
	v_mov_b32_e32 v86, v29
	v_mov_b32_e32 v87, v13
	v_pk_fma_f32 v[84:85], v[86:87], v[86:87], v[84:85]
	v_mov_b32_e32 v86, v7
	v_add_f32_e32 v84, v88, v84
	s_waitcnt vmcnt(0)
; __device__ __forceinline__ unsigned cvt_pk_bf16(float lo, float hi) { const f32x2 v = {lo, hi}; const bf16x2_t b = __builtin_convertvector(v, bf16x2_t); return __builtin_bit_cast(unsigned, b); }
; __device__ __forceinline__ void norm_rows(const XSrc src, const float* gain, bf16_t* dbf, float* df32) {
;     ...
;         for (int o = 32; o > 0; o >>= 1) { ss += __shfl_xor(ss, o); st += __shfl_xor(st, o); }
;         const float rs = 1.0f / sqrtf(ss * (1.0f / DM) + 1e-6f), rt = 1.0f / sqrtf(st * (1.0f / DM) + 1e-6f);
; #pragma unroll
;         for (int i = 0; i < 8; ++i) {
;             const f32x4 gn = *(const f32x4*)(gain + i * 256 + lane * 4);
;             const f32x4 y = v[i] * rs * gn, y2 = u[i] * rt * gn;
;             if (dbf) { u32x2 w; w.x = cvt_pk_bf16(y[0], y[1]); w.y = cvt_pk_bf16(y[2], y[3]); *(u32x2*)(dbf + (size_t)row * DM + i * 256 + lane * 4) = w;
;                        if (row2 != row) { w.x = cvt_pk_bf16(y2[0], y2[1]); w.y = cvt_pk_bf16(y2[2], y2[3]); *(u32x2*)(dbf + (size_t)row2 * DM + i * 256 + lane * 4) = w; } }
;             if (df32) { *(f32x4*)(df32 + (size_t)row * DM + i * 256 + lane * 4) = y; if (row2 != row) *(f32x4*)(df32 + (size_t)row2 * DM + i * 256 + lane * 4) = y2; }
	v_mov_b32_e32 v87, v3
	v_add_f32_e32 v88, v84, v85
	v_mov_b32_e32 v84, v6
	v_mov_b32_e32 v85, v2
	v_pk_mul_f32 v[86:87], v[86:87], v[86:87]
	s_nop 0
	v_pk_fma_f32 v[84:85], v[84:85], v[84:85], v[86:87]
	v_mov_b32_e32 v86, v8
	v_mov_b32_e32 v87, v4
	v_pk_fma_f32 v[84:85], v[86:87], v[86:87], v[84:85]
	v_mov_b32_e32 v86, v9
	v_mov_b32_e32 v87, v5
	v_pk_fma_f32 v[84:85], v[86:87], v[86:87], v[84:85]
	s_nop 0
	v_add_f32_e32 v84, v89, v84
	v_add_f32_e32 v84, v84, v85
	ds_bpermute_b32 v85, v92, v88
	ds_bpermute_b32 v86, v92, v84
	s_waitcnt lgkmcnt(1)
	v_add_f32_e32 v85, v88, v85
	s_waitcnt lgkmcnt(0)
	v_add_f32_e32 v84, v84, v86
	ds_bpermute_b32 v86, v93, v85
	s_waitcnt lgkmcnt(0)
	v_add_f32_e32 v85, v85, v86
	ds_bpermute_b32 v86, v93, v84
	s_waitcnt lgkmcnt(0)
	v_add_f32_e32 v84, v84, v86
	ds_bpermute_b32 v86, v94, v85
	s_waitcnt lgkmcnt(0)
	v_add_f32_e32 v85, v85, v86
	ds_bpermute_b32 v86, v94, v84
	s_waitcnt lgkmcnt(0)
	v_add_f32_e32 v84, v84, v86
	ds_bpermute_b32 v86, v95, v85
	s_waitcnt lgkmcnt(0)
	v_add_f32_e32 v85, v85, v86
	ds_bpermute_b32 v86, v95, v84
	s_waitcnt lgkmcnt(0)
	v_add_f32_e32 v84, v84, v86
	ds_bpermute_b32 v86, v96, v85
	s_waitcnt lgkmcnt(0)
	v_add_f32_e32 v85, v85, v86
	ds_bpermute_b32 v86, v96, v84
	s_waitcnt lgkmcnt(0)
	v_add_f32_e32 v84, v84, v86
	ds_bpermute_b32 v86, v97, v85
	s_waitcnt lgkmcnt(0)
	v_add_f32_e32 v85, v85, v86
	ds_bpermute_b32 v86, v97, v84
	s_waitcnt lgkmcnt(0)
	v_add_f32_e32 v86, v84, v86
	v_fmamk_f32 v84, v85, 0x3a000000, v183
	v_cmp_gt_f32_e32 vcc, s6, v84
	v_mul_f32_e32 v85, 0x4f800000, v84
	s_nop 0
	v_cndmask_b32_e32 v84, v84, v85, vcc
	v_sqrt_f32_e32 v85, v84
	s_nop 0
	v_add_u32_e32 v87, -1, v85
	v_fma_f32 v88, -v87, v85, v84
	v_cmp_ge_f32_e64 s[4:5], 0, v88
	v_add_u32_e32 v88, 1, v85
	s_nop 0
	v_cndmask_b32_e64 v87, v85, v87, s[4:5]
	v_fma_f32 v85, -v88, v85, v84
	v_cmp_lt_f32_e64 s[4:5], 0, v85
	s_nop 1
	v_cndmask_b32_e64 v85, v87, v88, s[4:5]
	v_mul_f32_e32 v87, 0x37800000, v85
	v_cndmask_b32_e32 v85, v85, v87, vcc
	v_cmp_class_f32_e32 vcc, v84, v184
	s_nop 1
	v_cndmask_b32_e32 v84, v85, v84, vcc
	v_div_scale_f32 v85, s[4:5], v84, v84, 1.0
	v_rcp_f32_e32 v87, v85
	s_nop 0
	v_fma_f32 v88, -v85, v87, 1.0
	v_fmac_f32_e32 v87, v88, v87
	v_div_scale_f32 v88, vcc, 1.0, v84, 1.0
	v_mul_f32_e32 v89, v88, v87
	v_fma_f32 v90, -v85, v89, v88
	v_fmac_f32_e32 v89, v90, v87
	v_fma_f32 v85, -v85, v89, v88
	v_div_fmas_f32 v85, v85, v87, v89
	v_div_fixup_f32 v84, v85, v84, 1.0
	v_fmamk_f32 v85, v86, 0x3a000000, v183
	v_cmp_gt_f32_e32 vcc, s6, v85
	v_mul_f32_e32 v86, 0x4f800000, v85
	s_nop 0
	v_cndmask_b32_e32 v85, v85, v86, vcc
	v_sqrt_f32_e32 v86, v85
	s_nop 0
	v_add_u32_e32 v87, -1, v86
	v_fma_f32 v88, -v87, v86, v85
	v_cmp_ge_f32_e64 s[4:5], 0, v88
	v_add_u32_e32 v88, 1, v86
	s_nop 0
	v_cndmask_b32_e64 v87, v86, v87, s[4:5]
	v_fma_f32 v86, -v88, v86, v85
	v_cmp_lt_f32_e64 s[4:5], 0, v86
	s_nop 1
	v_cndmask_b32_e64 v86, v87, v88, s[4:5]
	v_mul_f32_e32 v87, 0x37800000, v86
	v_cndmask_b32_e32 v86, v86, v87, vcc
	v_cmp_class_f32_e32 vcc, v85, v184
	s_nop 1
	v_cndmask_b32_e32 v85, v86, v85, vcc
	v_div_scale_f32 v86, s[4:5], v85, v85, 1.0
	v_rcp_f32_e32 v87, v86
	v_pk_mul_f32 v[62:63], v[62:63], v[84:85] op_sel_hi:[1,0]
	v_pk_mul_f32 v[64:65], v[64:65], v[84:85] op_sel_hi:[1,0]
	v_fma_f32 v88, -v86, v87, 1.0
	v_fmac_f32_e32 v87, v88, v87
	v_div_scale_f32 v88, vcc, 1.0, v85, 1.0
	v_mul_f32_e32 v89, v88, v87
	v_fma_f32 v90, -v86, v89, v88
	v_fmac_f32_e32 v89, v90, v87
	v_fma_f32 v86, -v86, v89, v88
	v_div_fmas_f32 v86, v86, v87, v89
	v_div_fixup_f32 v88, v86, v85, 1.0
	v_lshlrev_b64 v[86:87], 12, v[66:67]
	v_cmp_ne_u32_e32 vcc, v66, v68
	v_lshlrev_b64 v[66:67], 12, v[68:69]
	v_lshl_add_u64 v[90:91], v[72:73], 0, v[86:87]
	v_lshl_add_u64 v[86:87], v[72:73], 0, v[66:67]
	v_mov_b32_e32 v89, v88
	v_pk_mul_f32 v[64:65], v[198:199], v[64:65]
	v_pk_mul_f32 v[62:63], v[196:197], v[62:63]
	s_nop 0
	v_cvt_pk_bf16_f32 v62, v62, v63
	v_cvt_pk_bf16_f32 v63, v64, v65
	global_store_dwordx2 v[90:91], v[62:63], off
	s_and_saveexec_b64 s[4:5], vcc
	s_cbranch_execz .LBB0_1767
	v_mov_b32_e32 v62, v88
	v_mov_b32_e32 v63, v88
	v_pk_mul_f32 v[60:61], v[60:61], v[62:63]
	v_pk_mul_f32 v[58:59], v[58:59], v[88:89]
	v_pk_mul_f32 v[60:61], v[198:199], v[60:61]
	v_pk_mul_f32 v[58:59], v[196:197], v[58:59]
	s_nop 0
	v_cvt_pk_bf16_f32 v58, v58, v59
	v_cvt_pk_bf16_f32 v59, v60, v61
	global_store_dwordx2 v[86:87], v[58:59], off
